# v8 + hyena FFT stride-4 radix-4 levels rewritten by hand: lane-rotated conflict-free LDS access, rotation folded into per-lane unit twiddle factors (f32 packed math, same as baseline)
# speedup vs baseline: 1.0078x; 1.0015x over previous
; DI float2 twid(float r) { return float2{__builtin_amdgcn_cosf(r), -__builtin_amdgcn_sinf(r)}; }
; DI void bfly_fwd(float2 a0, float2 a1, float2 a2, float2 a3, float r, float2& o0, float2& o1, float2& o2, float2& o3) {
;   float2 t0 = {a0.x + a2.x, a0.y + a2.y}, t1 = {a0.x - a2.x, a0.y - a2.y}, t2 = {a1.x + a3.x, a1.y + a3.y}, t3 = {a1.x - a3.x, a1.y - a3.y};
;   float2 b0 = {t0.x + t2.x, t0.y + t2.y}, b2 = {t0.x - t2.x, t0.y - t2.y}, b1 = {t1.x + t3.y, t1.y - t3.x}, b3 = {t1.x - t3.y, t1.y + t3.x};
;   float2 w1 = twid(r), w2 = cmul(w1, w1), w3 = cmul(w2, w1);
;   o0 = b0; o1 = cmul(b1, w1); o2 = cmul(b2, w2); o3 = cmul(b3, w3);
; }
;   const int Q = 1 << lq; const float invM = 1.f / (float)(4 << lq);
;   for (int bb = tid; bb < NBT * (N / 4); bb += NTHR) { const int b = bb & (N / 4 - 1); float2* z = z0 + (bb / (N / 4)) * N; int j = b & (Q - 1), base = ((b >> lq) << (lq + 2)) + j; float2 o0, o1, o2, o3;
;     bfly_fwd(z[base], z[base + Q], z[base + 2 * Q], z[base + 3 * Q], (float)j * invM, o0, o1, o2, o3);
;     z[base] = o0; z[base + Q] = o1; z[base + 2 * Q] = o2; z[base + 3 * Q] = o3; }
;   __syncthreads();
.LBB0_1494:
	s_or_b64 exec, exec, s[0:1]
	s_movk_i32 s0, 0x800
	v_cmp_gt_i32_e32 vcc, s0, v10
	v_lshlrev_b32_e32 v11, 2, v10
	s_waitcnt lgkmcnt(0)
	s_barrier
	s_and_saveexec_b64 s[0:1], vcc
	s_cbranch_execz .LBB0_1497
	v_and_b32_e32 v24, 3, v10
	v_cvt_f32_ubyte0_e32 v12, v24
	v_mul_f32_e32 v13, 0x3d800000, v12
	v_sin_f32_e32 v12, v13
	v_cos_f32_e32 v14, v13
	v_lshlrev_b32_e32 v25, 2, v10
	s_mov_b64 s[10:11], 0
	v_mul_f32_e32 v13, v12, v12
	v_mul_f32_e64 v15, v14, -v12
	v_fma_f32 v16, v14, v14, -v13
	v_add_f32_e32 v18, v15, v15
	v_mul_f32_e32 v20, v12, v18
	v_mul_f32_e32 v13, v12, v16
	v_fmac_f32_e32 v20, v14, v16
	v_fma_f32 v22, v14, v18, -v13
	v_mov_b32_e32 v15, v14
	v_mov_b32_e32 v13, v12
	v_mov_b32_e32 v17, v16
	v_mov_b32_e32 v21, v20
	v_mov_b32_e32 v23, v22
	v_mov_b32_e32 v19, v18
	v_mov_b32_e32 v26, v10
	v_and_b32_e32 v244, 3, v26
	v_cvt_f32_u32_e32 v244, v244
	v_mul_f32_e32 v244, 0x3d800000, v244
	v_cos_f32_e32 v218, v244
	v_sin_f32_e32 v219, v244
	s_nop 1
	v_xor_b32_e32 v219, 0x80000000, v219
	s_nop 0
	v_pk_mul_f32 v[42:43], v[218:219], v[218:219] op_sel:[1,1] op_sel_hi:[1,0]
	s_nop 0
	v_pk_fma_f32 v[220:221], v[218:219], v[218:219], v[42:43] op_sel_hi:[0,1,1] neg_lo:[0,0,1]
	s_nop 0
	v_pk_mul_f32 v[42:43], v[220:221], v[218:219] op_sel:[1,1] op_sel_hi:[1,0]
	s_nop 0
	v_pk_fma_f32 v[36:37], v[220:221], v[218:219], v[42:43] op_sel_hi:[0,1,1] neg_lo:[0,0,1]
	s_nop 0
	v_bfe_u32 v241, v26, 2, 2
	v_bfe_u32 v244, v26, 4, 1
	v_add_u32_e32 v241, v241, v244
	v_and_b32_e32 v241, 3, v241
	v_add_u32_e32 v244, 0, v241
	v_and_b32_e32 v244, 3, v244
	v_lshlrev_b32_e32 v236, 5, v244
	v_add_u32_e32 v244, 1, v241
	v_and_b32_e32 v244, 3, v244
	v_lshlrev_b32_e32 v237, 5, v244
	v_add_u32_e32 v244, 2, v241
	v_and_b32_e32 v244, 3, v244
	v_lshlrev_b32_e32 v238, 5, v244
	v_add_u32_e32 v244, 3, v241
	v_and_b32_e32 v244, 3, v244
	v_lshlrev_b32_e32 v239, 5, v244
	v_mul_u32_u24_e32 v243, 1, v241
	v_and_b32_e32 v243, 3, v243
	v_cmp_eq_u32_e64 s[8:9], 0, v243
	s_nop 3
	v_cndmask_b32_e64 v222, 0, 1.0, s[8:9]
	v_cmp_eq_u32_e64 s[8:9], 2, v243
	s_nop 3
	v_cndmask_b32_e64 v222, v222, -1.0, s[8:9]
	v_cmp_eq_u32_e64 s[8:9], 1, v243
	s_nop 3
	v_cndmask_b32_e64 v223, 0, -1.0, s[8:9]
	v_cmp_eq_u32_e64 s[8:9], 3, v243
	s_nop 3
	v_cndmask_b32_e64 v223, v223, 1.0, s[8:9]
	v_mul_u32_u24_e32 v243, 2, v241
	v_and_b32_e32 v243, 3, v243
	v_cmp_eq_u32_e64 s[8:9], 0, v243
	s_nop 3
	v_cndmask_b32_e64 v224, 0, 1.0, s[8:9]
	v_cmp_eq_u32_e64 s[8:9], 2, v243
	s_nop 3
	v_cndmask_b32_e64 v224, v224, -1.0, s[8:9]
	v_cmp_eq_u32_e64 s[8:9], 1, v243
	s_nop 3
	v_cndmask_b32_e64 v225, 0, -1.0, s[8:9]
	v_cmp_eq_u32_e64 s[8:9], 3, v243
	s_nop 3
	v_cndmask_b32_e64 v225, v225, 1.0, s[8:9]
	v_mul_u32_u24_e32 v243, 3, v241
	v_and_b32_e32 v243, 3, v243
	v_cmp_eq_u32_e64 s[8:9], 0, v243
	s_nop 3
	v_cndmask_b32_e64 v226, 0, 1.0, s[8:9]
	v_cmp_eq_u32_e64 s[8:9], 2, v243
	s_nop 3
	v_cndmask_b32_e64 v226, v226, -1.0, s[8:9]
	v_cmp_eq_u32_e64 s[8:9], 1, v243
	s_nop 3
	v_cndmask_b32_e64 v227, 0, -1.0, s[8:9]
	v_cmp_eq_u32_e64 s[8:9], 3, v243
	s_nop 3
	v_cndmask_b32_e64 v227, v227, 1.0, s[8:9]
	v_add_u32_e32 v242, 0, v241
	v_and_b32_e32 v242, 3, v242
	v_mov_b32_e32 v38, 1.0
	v_mov_b32_e32 v39, 0
	v_cmp_eq_u32_e64 s[8:9], 1, v242
	s_nop 3
	v_cndmask_b32_e64 v38, v38, v218, s[8:9]
	v_cndmask_b32_e64 v39, v39, v219, s[8:9]
	v_cmp_eq_u32_e64 s[8:9], 2, v242
	s_nop 3
	v_cndmask_b32_e64 v38, v38, v220, s[8:9]
	v_cndmask_b32_e64 v39, v39, v221, s[8:9]
	v_cmp_eq_u32_e64 s[8:9], 3, v242
	s_nop 3
	v_cndmask_b32_e64 v38, v38, v36, s[8:9]
	v_cndmask_b32_e64 v39, v39, v37, s[8:9]
	v_add_u32_e32 v243, 0, v241
	v_mul_u32_u24_e32 v243, v243, v241
	v_and_b32_e32 v243, 3, v243
	v_cmp_eq_u32_e64 s[8:9], 0, v243
	s_nop 3
	v_cndmask_b32_e64 v40, 0, 1.0, s[8:9]
	v_cmp_eq_u32_e64 s[8:9], 2, v243
	s_nop 3
	v_cndmask_b32_e64 v40, v40, -1.0, s[8:9]
	v_cmp_eq_u32_e64 s[8:9], 1, v243
	s_nop 3
	v_cndmask_b32_e64 v41, 0, -1.0, s[8:9]
	v_cmp_eq_u32_e64 s[8:9], 3, v243
	s_nop 3
	v_cndmask_b32_e64 v41, v41, 1.0, s[8:9]
	v_pk_mul_f32 v[42:43], v[38:39], v[40:41] op_sel:[1,1] op_sel_hi:[1,0]
	s_nop 0
	v_pk_fma_f32 v[228:229], v[38:39], v[40:41], v[42:43] op_sel_hi:[0,1,1] neg_lo:[0,0,1]
	s_nop 0
	v_add_u32_e32 v242, 1, v241
	v_and_b32_e32 v242, 3, v242
	v_mov_b32_e32 v38, 1.0
	v_mov_b32_e32 v39, 0
	v_cmp_eq_u32_e64 s[8:9], 1, v242
	s_nop 3
	v_cndmask_b32_e64 v38, v38, v218, s[8:9]
	v_cndmask_b32_e64 v39, v39, v219, s[8:9]
	v_cmp_eq_u32_e64 s[8:9], 2, v242
	s_nop 3
	v_cndmask_b32_e64 v38, v38, v220, s[8:9]
	v_cndmask_b32_e64 v39, v39, v221, s[8:9]
	v_cmp_eq_u32_e64 s[8:9], 3, v242
	s_nop 3
	v_cndmask_b32_e64 v38, v38, v36, s[8:9]
	v_cndmask_b32_e64 v39, v39, v37, s[8:9]
	v_add_u32_e32 v243, 1, v241
	v_mul_u32_u24_e32 v243, v243, v241
	v_and_b32_e32 v243, 3, v243
	v_cmp_eq_u32_e64 s[8:9], 0, v243
	s_nop 3
	v_cndmask_b32_e64 v40, 0, 1.0, s[8:9]
	v_cmp_eq_u32_e64 s[8:9], 2, v243
	s_nop 3
	v_cndmask_b32_e64 v40, v40, -1.0, s[8:9]
	v_cmp_eq_u32_e64 s[8:9], 1, v243
	s_nop 3
	v_cndmask_b32_e64 v41, 0, -1.0, s[8:9]
; DI float2 twid(float r) { return float2{__builtin_amdgcn_cosf(r), -__builtin_amdgcn_sinf(r)}; }
; DI void bfly_fwd(float2 a0, float2 a1, float2 a2, float2 a3, float r, float2& o0, float2& o1, float2& o2, float2& o3) {
;   float2 t0 = {a0.x + a2.x, a0.y + a2.y}, t1 = {a0.x - a2.x, a0.y - a2.y}, t2 = {a1.x + a3.x, a1.y + a3.y}, t3 = {a1.x - a3.x, a1.y - a3.y};
;   float2 b0 = {t0.x + t2.x, t0.y + t2.y}, b2 = {t0.x - t2.x, t0.y - t2.y}, b1 = {t1.x + t3.y, t1.y - t3.x}, b3 = {t1.x - t3.y, t1.y + t3.x};
;   float2 w1 = twid(r), w2 = cmul(w1, w1), w3 = cmul(w2, w1);
;   o0 = b0; o1 = cmul(b1, w1); o2 = cmul(b2, w2); o3 = cmul(b3, w3);
; }
;   const int Q = 1 << lq; const float invM = 1.f / (float)(4 << lq);
;   for (int bb = tid; bb < NBT * (N / 4); bb += NTHR) { const int b = bb & (N / 4 - 1); float2* z = z0 + (bb / (N / 4)) * N; int j = b & (Q - 1), base = ((b >> lq) << (lq + 2)) + j; float2 o0, o1, o2, o3;
;     bfly_fwd(z[base], z[base + Q], z[base + 2 * Q], z[base + 3 * Q], (float)j * invM, o0, o1, o2, o3);
;     z[base] = o0; z[base + Q] = o1; z[base + 2 * Q] = o2; z[base + 3 * Q] = o3; }
;   __syncthreads();
	v_cmp_eq_u32_e64 s[8:9], 3, v243
	s_nop 3
	v_cndmask_b32_e64 v41, v41, 1.0, s[8:9]
	v_pk_mul_f32 v[42:43], v[38:39], v[40:41] op_sel:[1,1] op_sel_hi:[1,0]
	s_nop 0
	v_pk_fma_f32 v[230:231], v[38:39], v[40:41], v[42:43] op_sel_hi:[0,1,1] neg_lo:[0,0,1]
	s_nop 0
	v_add_u32_e32 v242, 2, v241
	v_and_b32_e32 v242, 3, v242
	v_mov_b32_e32 v38, 1.0
	v_mov_b32_e32 v39, 0
	v_cmp_eq_u32_e64 s[8:9], 1, v242
	s_nop 3
	v_cndmask_b32_e64 v38, v38, v218, s[8:9]
	v_cndmask_b32_e64 v39, v39, v219, s[8:9]
	v_cmp_eq_u32_e64 s[8:9], 2, v242
	s_nop 3
	v_cndmask_b32_e64 v38, v38, v220, s[8:9]
	v_cndmask_b32_e64 v39, v39, v221, s[8:9]
	v_cmp_eq_u32_e64 s[8:9], 3, v242
	s_nop 3
	v_cndmask_b32_e64 v38, v38, v36, s[8:9]
	v_cndmask_b32_e64 v39, v39, v37, s[8:9]
	v_add_u32_e32 v243, 2, v241
	v_mul_u32_u24_e32 v243, v243, v241
	v_and_b32_e32 v243, 3, v243
	v_cmp_eq_u32_e64 s[8:9], 0, v243
	s_nop 3
	v_cndmask_b32_e64 v40, 0, 1.0, s[8:9]
	v_cmp_eq_u32_e64 s[8:9], 2, v243
	s_nop 3
	v_cndmask_b32_e64 v40, v40, -1.0, s[8:9]
	v_cmp_eq_u32_e64 s[8:9], 1, v243
	s_nop 3
	v_cndmask_b32_e64 v41, 0, -1.0, s[8:9]
	v_cmp_eq_u32_e64 s[8:9], 3, v243
	s_nop 3
	v_cndmask_b32_e64 v41, v41, 1.0, s[8:9]
	v_pk_mul_f32 v[42:43], v[38:39], v[40:41] op_sel:[1,1] op_sel_hi:[1,0]
	s_nop 0
	v_pk_fma_f32 v[232:233], v[38:39], v[40:41], v[42:43] op_sel_hi:[0,1,1] neg_lo:[0,0,1]
	s_nop 0
	v_add_u32_e32 v242, 3, v241
	v_and_b32_e32 v242, 3, v242
	v_mov_b32_e32 v38, 1.0
	v_mov_b32_e32 v39, 0
	v_cmp_eq_u32_e64 s[8:9], 1, v242
	s_nop 3
	v_cndmask_b32_e64 v38, v38, v218, s[8:9]
	v_cndmask_b32_e64 v39, v39, v219, s[8:9]
	v_cmp_eq_u32_e64 s[8:9], 2, v242
	s_nop 3
	v_cndmask_b32_e64 v38, v38, v220, s[8:9]
	v_cndmask_b32_e64 v39, v39, v221, s[8:9]
	v_cmp_eq_u32_e64 s[8:9], 3, v242
	s_nop 3
	v_cndmask_b32_e64 v38, v38, v36, s[8:9]
	v_cndmask_b32_e64 v39, v39, v37, s[8:9]
	v_add_u32_e32 v243, 3, v241
	v_mul_u32_u24_e32 v243, v243, v241
	v_and_b32_e32 v243, 3, v243
	v_cmp_eq_u32_e64 s[8:9], 0, v243
	s_nop 3
	v_cndmask_b32_e64 v40, 0, 1.0, s[8:9]
	v_cmp_eq_u32_e64 s[8:9], 2, v243
	s_nop 3
	v_cndmask_b32_e64 v40, v40, -1.0, s[8:9]
	v_cmp_eq_u32_e64 s[8:9], 1, v243
	s_nop 3
	v_cndmask_b32_e64 v41, 0, -1.0, s[8:9]
	v_cmp_eq_u32_e64 s[8:9], 3, v243
	s_nop 3
	v_cndmask_b32_e64 v41, v41, 1.0, s[8:9]
	v_pk_mul_f32 v[42:43], v[38:39], v[40:41] op_sel:[1,1] op_sel_hi:[1,0]
	s_nop 0
	v_pk_fma_f32 v[234:235], v[38:39], v[40:41], v[42:43] op_sel_hi:[0,1,1] neg_lo:[0,0,1]
	s_nop 0
.LBB0_1496:
	v_ashrrev_i32_e32 v27, 31, v26
	v_lshrrev_b32_e32 v27, 21, v27
	v_add_lshl_u32 v27, v26, v27, 5
	v_and_b32_e32 v27, 0xffff0000, v27
	v_and_b32_e32 v28, 0x1ff0, v25
	v_add_u32_e32 v27, 16, v27
	v_lshlrev_b32_e32 v28, 3, v28
	v_lshlrev_b32_e32 v29, 3, v24
	v_add3_u32 v27, v27, v28, v29
	v_add_u32_e32 v241, v27, v236
	v_add_u32_e32 v242, v27, v237
	v_add_u32_e32 v243, v27, v238
	v_add_u32_e32 v244, v27, v239
	ds_read_b64 v[28:29], v241
	ds_read_b64 v[30:31], v242
	ds_read_b64 v[32:33], v243
	ds_read_b64 v[34:35], v244
	v_cmp_lt_i32_e64 s[8:9], s3, v26
	v_add_u32_e32 v25, 0x800, v25
	s_or_b64 s[10:11], s[8:9], s[10:11]
	s_waitcnt lgkmcnt(0)
	v_pk_mul_f32 v[218:219], v[30:31], v[222:223] op_sel:[1,1] op_sel_hi:[1,0]
	v_pk_mul_f32 v[220:221], v[32:33], v[224:225] op_sel:[1,1] op_sel_hi:[1,0]
	v_pk_mul_f32 v[36:37], v[34:35], v[226:227] op_sel:[1,1] op_sel_hi:[1,0]
	v_pk_fma_f32 v[30:31], v[30:31], v[222:223], v[218:219] op_sel_hi:[0,1,1] neg_lo:[0,0,1]
	v_pk_fma_f32 v[32:33], v[32:33], v[224:225], v[220:221] op_sel_hi:[0,1,1] neg_lo:[0,0,1]
	v_pk_fma_f32 v[34:35], v[34:35], v[226:227], v[36:37] op_sel_hi:[0,1,1] neg_lo:[0,0,1]
	v_pk_add_f32 v[36:37], v[28:29], v[32:33]
	v_pk_add_f32 v[38:39], v[28:29], v[32:33] neg_lo:[0,1] neg_hi:[0,1]
	v_pk_add_f32 v[40:41], v[30:31], v[34:35]
	v_pk_add_f32 v[42:43], v[30:31], v[34:35] neg_lo:[0,1] neg_hi:[0,1]
	v_pk_add_f32 v[28:29], v[36:37], v[40:41]
	v_pk_add_f32 v[32:33], v[36:37], v[40:41] neg_lo:[0,1] neg_hi:[0,1]
	v_pk_add_f32 v[30:31], v[38:39], v[42:43] op_sel:[0,1] op_sel_hi:[1,0] neg_hi:[0,1]
	v_pk_add_f32 v[34:35], v[38:39], v[42:43] op_sel:[0,1] op_sel_hi:[1,0] neg_lo:[0,1]
	v_pk_mul_f32 v[218:219], v[28:29], v[228:229] op_sel:[1,1] op_sel_hi:[1,0]
	v_pk_mul_f32 v[220:221], v[32:33], v[232:233] op_sel:[1,1] op_sel_hi:[1,0]
	v_pk_mul_f32 v[36:37], v[30:31], v[230:231] op_sel:[1,1] op_sel_hi:[1,0]
	v_pk_mul_f32 v[40:41], v[34:35], v[234:235] op_sel:[1,1] op_sel_hi:[1,0]
	v_pk_fma_f32 v[28:29], v[28:29], v[228:229], v[218:219] op_sel_hi:[0,1,1] neg_lo:[0,0,1]
	v_pk_fma_f32 v[32:33], v[32:33], v[232:233], v[220:221] op_sel_hi:[0,1,1] neg_lo:[0,0,1]
	v_pk_fma_f32 v[30:31], v[30:31], v[230:231], v[36:37] op_sel_hi:[0,1,1] neg_lo:[0,0,1]
	v_pk_fma_f32 v[34:35], v[34:35], v[234:235], v[40:41] op_sel_hi:[0,1,1] neg_lo:[0,0,1]
	s_nop 0
	ds_write_b64 v241, v[28:29]
	ds_write_b64 v243, v[32:33]
	ds_write_b64 v242, v[30:31]
	ds_write_b64 v244, v[34:35]
	v_add_u32_e32 v27, 0x200, v26
	v_mov_b32_e32 v26, v27
	s_andn2_b64 exec, exec, s[10:11]
	s_cbranch_execnz .LBB0_1496

; DI float2 twid(float r) { return float2{__builtin_amdgcn_cosf(r), -__builtin_amdgcn_sinf(r)}; }
; DI void bfly_fwd(float2 a0, float2 a1, float2 a2, float2 a3, float r, float2& o0, float2& o1, float2& o2, float2& o3) {
;   float2 t0 = {a0.x + a2.x, a0.y + a2.y}, t1 = {a0.x - a2.x, a0.y - a2.y}, t2 = {a1.x + a3.x, a1.y + a3.y}, t3 = {a1.x - a3.x, a1.y - a3.y};
;   float2 b0 = {t0.x + t2.x, t0.y + t2.y}, b2 = {t0.x - t2.x, t0.y - t2.y}, b1 = {t1.x + t3.y, t1.y - t3.x}, b3 = {t1.x - t3.y, t1.y + t3.x};
;   float2 w1 = twid(r), w2 = cmul(w1, w1), w3 = cmul(w2, w1);
;   o0 = b0; o1 = cmul(b1, w1); o2 = cmul(b2, w2); o3 = cmul(b3, w3);
; }
;   const int Q = 1 << lq; const float invM = 1.f / (float)(4 << lq);
;   for (int bb = tid; bb < NBT * (N / 4); bb += NTHR) { const int b = bb & (N / 4 - 1); float2* z = z0 + (bb / (N / 4)) * N; int j = b & (Q - 1), base = ((b >> lq) << (lq + 2)) + j; float2 o0, o1, o2, o3;
;     bfly_fwd(z[base], z[base + Q], z[base + 2 * Q], z[base + 3 * Q], (float)j * invM, o0, o1, o2, o3);
;     z[base] = o0; z[base + Q] = o1; z[base + 2 * Q] = o2; z[base + 3 * Q] = o3; }
;   __syncthreads();
.LBB0_1522:
	s_or_b64 exec, exec, s[0:1]
	v_lshlrev_b32_e32 v11, 2, v10
	s_waitcnt lgkmcnt(0)
	s_barrier
	s_and_saveexec_b64 s[0:1], s[8:9]
	s_cbranch_execz .LBB0_1525
	v_and_b32_e32 v24, 3, v10
	v_cvt_f32_ubyte0_e32 v12, v24
	v_mul_f32_e32 v13, 0x3d800000, v12
	v_sin_f32_e32 v12, v13
	v_cos_f32_e32 v14, v13
	v_lshlrev_b32_e32 v25, 2, v10
	s_mov_b64 s[10:11], 0
	v_mul_f32_e32 v13, v12, v12
	v_mul_f32_e64 v15, v14, -v12
	v_fma_f32 v16, v14, v14, -v13
	v_add_f32_e32 v18, v15, v15
	v_mul_f32_e32 v20, v12, v18
	v_mul_f32_e32 v13, v12, v16
	v_fmac_f32_e32 v20, v14, v16
	v_fma_f32 v22, v14, v18, -v13
	v_mov_b32_e32 v15, v14
	v_mov_b32_e32 v13, v12
	v_mov_b32_e32 v17, v16
	v_mov_b32_e32 v21, v20
	v_mov_b32_e32 v23, v22
	v_mov_b32_e32 v19, v18
	v_mov_b32_e32 v26, v10
	v_and_b32_e32 v244, 3, v26
	v_cvt_f32_u32_e32 v244, v244
	v_mul_f32_e32 v244, 0x3d800000, v244
	v_cos_f32_e32 v218, v244
	v_sin_f32_e32 v219, v244
	s_nop 1
	v_xor_b32_e32 v219, 0x80000000, v219
	s_nop 0
	v_pk_mul_f32 v[42:43], v[218:219], v[218:219] op_sel:[1,1] op_sel_hi:[1,0]
	s_nop 0
	v_pk_fma_f32 v[220:221], v[218:219], v[218:219], v[42:43] op_sel_hi:[0,1,1] neg_lo:[0,0,1]
	s_nop 0
	v_pk_mul_f32 v[42:43], v[220:221], v[218:219] op_sel:[1,1] op_sel_hi:[1,0]
	s_nop 0
	v_pk_fma_f32 v[36:37], v[220:221], v[218:219], v[42:43] op_sel_hi:[0,1,1] neg_lo:[0,0,1]
	s_nop 0
	v_bfe_u32 v241, v26, 2, 2
	v_bfe_u32 v244, v26, 4, 1
	v_add_u32_e32 v241, v241, v244
	v_and_b32_e32 v241, 3, v241
	v_add_u32_e32 v244, 0, v241
	v_and_b32_e32 v244, 3, v244
	v_lshlrev_b32_e32 v236, 5, v244
	v_add_u32_e32 v244, 1, v241
	v_and_b32_e32 v244, 3, v244
	v_lshlrev_b32_e32 v237, 5, v244
	v_add_u32_e32 v244, 2, v241
	v_and_b32_e32 v244, 3, v244
	v_lshlrev_b32_e32 v238, 5, v244
	v_add_u32_e32 v244, 3, v241
	v_and_b32_e32 v244, 3, v244
	v_lshlrev_b32_e32 v239, 5, v244
	v_mul_u32_u24_e32 v243, 1, v241
	v_and_b32_e32 v243, 3, v243
	v_cmp_eq_u32_e64 vcc, 0, v243
	s_nop 3
	v_cndmask_b32_e64 v222, 0, 1.0, vcc
	v_cmp_eq_u32_e64 vcc, 2, v243
	s_nop 3
	v_cndmask_b32_e64 v222, v222, -1.0, vcc
	v_cmp_eq_u32_e64 vcc, 1, v243
	s_nop 3
	v_cndmask_b32_e64 v223, 0, -1.0, vcc
	v_cmp_eq_u32_e64 vcc, 3, v243
	s_nop 3
	v_cndmask_b32_e64 v223, v223, 1.0, vcc
	v_mul_u32_u24_e32 v243, 2, v241
	v_and_b32_e32 v243, 3, v243
	v_cmp_eq_u32_e64 vcc, 0, v243
	s_nop 3
	v_cndmask_b32_e64 v224, 0, 1.0, vcc
	v_cmp_eq_u32_e64 vcc, 2, v243
	s_nop 3
	v_cndmask_b32_e64 v224, v224, -1.0, vcc
	v_cmp_eq_u32_e64 vcc, 1, v243
	s_nop 3
	v_cndmask_b32_e64 v225, 0, -1.0, vcc
	v_cmp_eq_u32_e64 vcc, 3, v243
	s_nop 3
	v_cndmask_b32_e64 v225, v225, 1.0, vcc
	v_mul_u32_u24_e32 v243, 3, v241
	v_and_b32_e32 v243, 3, v243
	v_cmp_eq_u32_e64 vcc, 0, v243
	s_nop 3
	v_cndmask_b32_e64 v226, 0, 1.0, vcc
	v_cmp_eq_u32_e64 vcc, 2, v243
	s_nop 3
	v_cndmask_b32_e64 v226, v226, -1.0, vcc
	v_cmp_eq_u32_e64 vcc, 1, v243
	s_nop 3
	v_cndmask_b32_e64 v227, 0, -1.0, vcc
	v_cmp_eq_u32_e64 vcc, 3, v243
	s_nop 3
	v_cndmask_b32_e64 v227, v227, 1.0, vcc
	v_add_u32_e32 v242, 0, v241
	v_and_b32_e32 v242, 3, v242
	v_mov_b32_e32 v38, 1.0
	v_mov_b32_e32 v39, 0
	v_cmp_eq_u32_e64 vcc, 1, v242
	s_nop 3
	v_cndmask_b32_e64 v38, v38, v218, vcc
	v_cndmask_b32_e64 v39, v39, v219, vcc
	v_cmp_eq_u32_e64 vcc, 2, v242
	s_nop 3
	v_cndmask_b32_e64 v38, v38, v220, vcc
	v_cndmask_b32_e64 v39, v39, v221, vcc
	v_cmp_eq_u32_e64 vcc, 3, v242
	s_nop 3
	v_cndmask_b32_e64 v38, v38, v36, vcc
	v_cndmask_b32_e64 v39, v39, v37, vcc
	v_add_u32_e32 v243, 0, v241
	v_mul_u32_u24_e32 v243, v243, v241
	v_and_b32_e32 v243, 3, v243
	v_cmp_eq_u32_e64 vcc, 0, v243
	s_nop 3
	v_cndmask_b32_e64 v40, 0, 1.0, vcc
	v_cmp_eq_u32_e64 vcc, 2, v243
	s_nop 3
	v_cndmask_b32_e64 v40, v40, -1.0, vcc
	v_cmp_eq_u32_e64 vcc, 1, v243
	s_nop 3
	v_cndmask_b32_e64 v41, 0, -1.0, vcc
	v_cmp_eq_u32_e64 vcc, 3, v243
	s_nop 3
	v_cndmask_b32_e64 v41, v41, 1.0, vcc
	v_pk_mul_f32 v[42:43], v[38:39], v[40:41] op_sel:[1,1] op_sel_hi:[1,0]
	s_nop 0
	v_pk_fma_f32 v[228:229], v[38:39], v[40:41], v[42:43] op_sel_hi:[0,1,1] neg_lo:[0,0,1]
	s_nop 0
	v_add_u32_e32 v242, 1, v241
	v_and_b32_e32 v242, 3, v242
	v_mov_b32_e32 v38, 1.0
	v_mov_b32_e32 v39, 0
	v_cmp_eq_u32_e64 vcc, 1, v242
	s_nop 3
	v_cndmask_b32_e64 v38, v38, v218, vcc
	v_cndmask_b32_e64 v39, v39, v219, vcc
	v_cmp_eq_u32_e64 vcc, 2, v242
	s_nop 3
	v_cndmask_b32_e64 v38, v38, v220, vcc
	v_cndmask_b32_e64 v39, v39, v221, vcc
	v_cmp_eq_u32_e64 vcc, 3, v242
	s_nop 3
	v_cndmask_b32_e64 v38, v38, v36, vcc
	v_cndmask_b32_e64 v39, v39, v37, vcc
	v_add_u32_e32 v243, 1, v241
	v_mul_u32_u24_e32 v243, v243, v241
	v_and_b32_e32 v243, 3, v243
	v_cmp_eq_u32_e64 vcc, 0, v243
	s_nop 3
	v_cndmask_b32_e64 v40, 0, 1.0, vcc
	v_cmp_eq_u32_e64 vcc, 2, v243
	s_nop 3
	v_cndmask_b32_e64 v40, v40, -1.0, vcc
	v_cmp_eq_u32_e64 vcc, 1, v243
	s_nop 3
	v_cndmask_b32_e64 v41, 0, -1.0, vcc
	v_cmp_eq_u32_e64 vcc, 3, v243
	s_nop 3
; DI float2 twid(float r) { return float2{__builtin_amdgcn_cosf(r), -__builtin_amdgcn_sinf(r)}; }
; DI void bfly_fwd(float2 a0, float2 a1, float2 a2, float2 a3, float r, float2& o0, float2& o1, float2& o2, float2& o3) {
;   float2 t0 = {a0.x + a2.x, a0.y + a2.y}, t1 = {a0.x - a2.x, a0.y - a2.y}, t2 = {a1.x + a3.x, a1.y + a3.y}, t3 = {a1.x - a3.x, a1.y - a3.y};
;   float2 b0 = {t0.x + t2.x, t0.y + t2.y}, b2 = {t0.x - t2.x, t0.y - t2.y}, b1 = {t1.x + t3.y, t1.y - t3.x}, b3 = {t1.x - t3.y, t1.y + t3.x};
;   float2 w1 = twid(r), w2 = cmul(w1, w1), w3 = cmul(w2, w1);
;   o0 = b0; o1 = cmul(b1, w1); o2 = cmul(b2, w2); o3 = cmul(b3, w3);
; }
;   const int Q = 1 << lq; const float invM = 1.f / (float)(4 << lq);
;   for (int bb = tid; bb < NBT * (N / 4); bb += NTHR) { const int b = bb & (N / 4 - 1); float2* z = z0 + (bb / (N / 4)) * N; int j = b & (Q - 1), base = ((b >> lq) << (lq + 2)) + j; float2 o0, o1, o2, o3;
;     bfly_fwd(z[base], z[base + Q], z[base + 2 * Q], z[base + 3 * Q], (float)j * invM, o0, o1, o2, o3);
;     z[base] = o0; z[base + Q] = o1; z[base + 2 * Q] = o2; z[base + 3 * Q] = o3; }
;   __syncthreads();
	v_cndmask_b32_e64 v41, v41, 1.0, vcc
	v_pk_mul_f32 v[42:43], v[38:39], v[40:41] op_sel:[1,1] op_sel_hi:[1,0]
	s_nop 0
	v_pk_fma_f32 v[230:231], v[38:39], v[40:41], v[42:43] op_sel_hi:[0,1,1] neg_lo:[0,0,1]
	s_nop 0
	v_add_u32_e32 v242, 2, v241
	v_and_b32_e32 v242, 3, v242
	v_mov_b32_e32 v38, 1.0
	v_mov_b32_e32 v39, 0
	v_cmp_eq_u32_e64 vcc, 1, v242
	s_nop 3
	v_cndmask_b32_e64 v38, v38, v218, vcc
	v_cndmask_b32_e64 v39, v39, v219, vcc
	v_cmp_eq_u32_e64 vcc, 2, v242
	s_nop 3
	v_cndmask_b32_e64 v38, v38, v220, vcc
	v_cndmask_b32_e64 v39, v39, v221, vcc
	v_cmp_eq_u32_e64 vcc, 3, v242
	s_nop 3
	v_cndmask_b32_e64 v38, v38, v36, vcc
	v_cndmask_b32_e64 v39, v39, v37, vcc
	v_add_u32_e32 v243, 2, v241
	v_mul_u32_u24_e32 v243, v243, v241
	v_and_b32_e32 v243, 3, v243
	v_cmp_eq_u32_e64 vcc, 0, v243
	s_nop 3
	v_cndmask_b32_e64 v40, 0, 1.0, vcc
	v_cmp_eq_u32_e64 vcc, 2, v243
	s_nop 3
	v_cndmask_b32_e64 v40, v40, -1.0, vcc
	v_cmp_eq_u32_e64 vcc, 1, v243
	s_nop 3
	v_cndmask_b32_e64 v41, 0, -1.0, vcc
	v_cmp_eq_u32_e64 vcc, 3, v243
	s_nop 3
	v_cndmask_b32_e64 v41, v41, 1.0, vcc
	v_pk_mul_f32 v[42:43], v[38:39], v[40:41] op_sel:[1,1] op_sel_hi:[1,0]
	s_nop 0
	v_pk_fma_f32 v[232:233], v[38:39], v[40:41], v[42:43] op_sel_hi:[0,1,1] neg_lo:[0,0,1]
	s_nop 0
	v_add_u32_e32 v242, 3, v241
	v_and_b32_e32 v242, 3, v242
	v_mov_b32_e32 v38, 1.0
	v_mov_b32_e32 v39, 0
	v_cmp_eq_u32_e64 vcc, 1, v242
	s_nop 3
	v_cndmask_b32_e64 v38, v38, v218, vcc
	v_cndmask_b32_e64 v39, v39, v219, vcc
	v_cmp_eq_u32_e64 vcc, 2, v242
	s_nop 3
	v_cndmask_b32_e64 v38, v38, v220, vcc
	v_cndmask_b32_e64 v39, v39, v221, vcc
	v_cmp_eq_u32_e64 vcc, 3, v242
	s_nop 3
	v_cndmask_b32_e64 v38, v38, v36, vcc
	v_cndmask_b32_e64 v39, v39, v37, vcc
	v_add_u32_e32 v243, 3, v241
	v_mul_u32_u24_e32 v243, v243, v241
	v_and_b32_e32 v243, 3, v243
	v_cmp_eq_u32_e64 vcc, 0, v243
	s_nop 3
	v_cndmask_b32_e64 v40, 0, 1.0, vcc
	v_cmp_eq_u32_e64 vcc, 2, v243
	s_nop 3
	v_cndmask_b32_e64 v40, v40, -1.0, vcc
	v_cmp_eq_u32_e64 vcc, 1, v243
	s_nop 3
	v_cndmask_b32_e64 v41, 0, -1.0, vcc
	v_cmp_eq_u32_e64 vcc, 3, v243
	s_nop 3
	v_cndmask_b32_e64 v41, v41, 1.0, vcc
	v_pk_mul_f32 v[42:43], v[38:39], v[40:41] op_sel:[1,1] op_sel_hi:[1,0]
	s_nop 0
	v_pk_fma_f32 v[234:235], v[38:39], v[40:41], v[42:43] op_sel_hi:[0,1,1] neg_lo:[0,0,1]
	s_nop 0
.LBB0_1524:
	v_ashrrev_i32_e32 v27, 31, v26
	v_lshrrev_b32_e32 v27, 20, v27
	v_add_lshl_u32 v27, v26, v27, 5
	v_and_b32_e32 v27, 0xfffe0000, v27
	v_and_b32_e32 v28, 0x3ff0, v25
	v_add_u32_e32 v27, 16, v27
	v_lshlrev_b32_e32 v28, 3, v28
	v_lshlrev_b32_e32 v29, 3, v24
	v_add3_u32 v27, v27, v28, v29
	v_add_u32_e32 v241, v27, v236
	v_add_u32_e32 v242, v27, v237
	v_add_u32_e32 v243, v27, v238
	v_add_u32_e32 v244, v27, v239
	ds_read_b64 v[28:29], v241
	ds_read_b64 v[30:31], v242
	ds_read_b64 v[32:33], v243
	ds_read_b64 v[34:35], v244
	v_cmp_lt_i32_e32 vcc, s25, v26
	v_add_u32_e32 v25, 0x800, v25
	s_or_b64 s[10:11], vcc, s[10:11]
	s_waitcnt lgkmcnt(0)
	v_pk_mul_f32 v[218:219], v[30:31], v[222:223] op_sel:[1,1] op_sel_hi:[1,0]
	v_pk_mul_f32 v[220:221], v[32:33], v[224:225] op_sel:[1,1] op_sel_hi:[1,0]
	v_pk_mul_f32 v[36:37], v[34:35], v[226:227] op_sel:[1,1] op_sel_hi:[1,0]
	v_pk_fma_f32 v[30:31], v[30:31], v[222:223], v[218:219] op_sel_hi:[0,1,1] neg_lo:[0,0,1]
	v_pk_fma_f32 v[32:33], v[32:33], v[224:225], v[220:221] op_sel_hi:[0,1,1] neg_lo:[0,0,1]
	v_pk_fma_f32 v[34:35], v[34:35], v[226:227], v[36:37] op_sel_hi:[0,1,1] neg_lo:[0,0,1]
	v_pk_add_f32 v[36:37], v[28:29], v[32:33]
	v_pk_add_f32 v[38:39], v[28:29], v[32:33] neg_lo:[0,1] neg_hi:[0,1]
	v_pk_add_f32 v[40:41], v[30:31], v[34:35]
	v_pk_add_f32 v[42:43], v[30:31], v[34:35] neg_lo:[0,1] neg_hi:[0,1]
	v_pk_add_f32 v[28:29], v[36:37], v[40:41]
	v_pk_add_f32 v[32:33], v[36:37], v[40:41] neg_lo:[0,1] neg_hi:[0,1]
	v_pk_add_f32 v[30:31], v[38:39], v[42:43] op_sel:[0,1] op_sel_hi:[1,0] neg_hi:[0,1]
	v_pk_add_f32 v[34:35], v[38:39], v[42:43] op_sel:[0,1] op_sel_hi:[1,0] neg_lo:[0,1]
	v_pk_mul_f32 v[218:219], v[28:29], v[228:229] op_sel:[1,1] op_sel_hi:[1,0]
	v_pk_mul_f32 v[220:221], v[32:33], v[232:233] op_sel:[1,1] op_sel_hi:[1,0]
	v_pk_mul_f32 v[36:37], v[30:31], v[230:231] op_sel:[1,1] op_sel_hi:[1,0]
	v_pk_mul_f32 v[40:41], v[34:35], v[234:235] op_sel:[1,1] op_sel_hi:[1,0]
	v_pk_fma_f32 v[28:29], v[28:29], v[228:229], v[218:219] op_sel_hi:[0,1,1] neg_lo:[0,0,1]
	v_pk_fma_f32 v[32:33], v[32:33], v[232:233], v[220:221] op_sel_hi:[0,1,1] neg_lo:[0,0,1]
	v_pk_fma_f32 v[30:31], v[30:31], v[230:231], v[36:37] op_sel_hi:[0,1,1] neg_lo:[0,0,1]
	v_pk_fma_f32 v[34:35], v[34:35], v[234:235], v[40:41] op_sel_hi:[0,1,1] neg_lo:[0,0,1]
	s_nop 0
	ds_write_b64 v241, v[28:29]
	ds_write_b64 v243, v[32:33]
	ds_write_b64 v242, v[30:31]
	ds_write_b64 v244, v[34:35]
	v_add_u32_e32 v27, 0x200, v26
	v_mov_b32_e32 v26, v27
	s_andn2_b64 exec, exec, s[10:11]
	s_cbranch_execnz .LBB0_1524

; DI float2 twid(float r) { return float2{__builtin_amdgcn_cosf(r), -__builtin_amdgcn_sinf(r)}; }
; DI void bfly_fwd(float2 a0, float2 a1, float2 a2, float2 a3, float r, float2& o0, float2& o1, float2& o2, float2& o3) {
;   float2 t0 = {a0.x + a2.x, a0.y + a2.y}, t1 = {a0.x - a2.x, a0.y - a2.y}, t2 = {a1.x + a3.x, a1.y + a3.y}, t3 = {a1.x - a3.x, a1.y - a3.y};
;   float2 b0 = {t0.x + t2.x, t0.y + t2.y}, b2 = {t0.x - t2.x, t0.y - t2.y}, b1 = {t1.x + t3.y, t1.y - t3.x}, b3 = {t1.x - t3.y, t1.y + t3.x};
;   float2 w1 = twid(r), w2 = cmul(w1, w1), w3 = cmul(w2, w1);
;   o0 = b0; o1 = cmul(b1, w1); o2 = cmul(b2, w2); o3 = cmul(b3, w3);
; }
;   const int Q = 1 << lq; const float invM = 1.f / (float)(4 << lq);
;   for (int bb = tid; bb < NBT * (N / 4); bb += NTHR) { const int b = bb & (N / 4 - 1); float2* z = z0 + (bb / (N / 4)) * N; int j = b & (Q - 1), base = ((b >> lq) << (lq + 2)) + j; float2 o0, o1, o2, o3;
;     bfly_fwd(z[base], z[base + Q], z[base + 2 * Q], z[base + 3 * Q], (float)j * invM, o0, o1, o2, o3);
;     z[base] = o0; z[base + Q] = o1; z[base + 2 * Q] = o2; z[base + 3 * Q] = o3; }
;   __syncthreads();
.LBB0_1604:
	s_or_b64 exec, exec, s[0:1]
	v_and_b32_e32 v14, 3, v75
	v_cvt_f32_ubyte0_e32 v16, v14
	v_lshlrev_b32_e32 v15, 2, v75
	s_waitcnt lgkmcnt(0)
	s_barrier
	s_and_saveexec_b64 s[0:1], s[10:11]
	s_cbranch_execz .LBB0_1607
	v_mul_f32_e32 v3, 0x3d800000, v16
	v_sin_f32_e32 v2, v3
	v_cos_f32_e32 v4, v3
	v_lshlrev_b32_e32 v17, 2, v75
	s_mov_b64 s[80:81], 0
	v_mul_f32_e32 v3, v2, v2
	v_mul_f32_e64 v5, v4, -v2
	v_fma_f32 v6, v4, v4, -v3
	v_add_f32_e32 v8, v5, v5
	v_mul_f32_e32 v10, v2, v8
	v_mul_f32_e32 v3, v2, v6
	v_fmac_f32_e32 v10, v4, v6
	v_fma_f32 v12, v4, v8, -v3
	v_mov_b32_e32 v5, v4
	v_mov_b32_e32 v3, v2
	v_mov_b32_e32 v7, v6
	v_mov_b32_e32 v11, v10
	v_mov_b32_e32 v13, v12
	v_mov_b32_e32 v9, v8
	v_mov_b32_e32 v18, v75
	v_and_b32_e32 v244, 3, v18
	v_cvt_f32_u32_e32 v244, v244
	v_mul_f32_e32 v244, 0x3d800000, v244
	v_cos_f32_e32 v218, v244
	v_sin_f32_e32 v219, v244
	s_nop 1
	v_xor_b32_e32 v219, 0x80000000, v219
	s_nop 0
	v_pk_mul_f32 v[34:35], v[218:219], v[218:219] op_sel:[1,1] op_sel_hi:[1,0]
	s_nop 0
	v_pk_fma_f32 v[220:221], v[218:219], v[218:219], v[34:35] op_sel_hi:[0,1,1] neg_lo:[0,0,1]
	s_nop 0
	v_pk_mul_f32 v[34:35], v[220:221], v[218:219] op_sel:[1,1] op_sel_hi:[1,0]
	s_nop 0
	v_pk_fma_f32 v[28:29], v[220:221], v[218:219], v[34:35] op_sel_hi:[0,1,1] neg_lo:[0,0,1]
	s_nop 0
	v_bfe_u32 v241, v18, 2, 2
	v_bfe_u32 v244, v18, 4, 1
	v_add_u32_e32 v241, v241, v244
	v_and_b32_e32 v241, 3, v241
	v_add_u32_e32 v244, 0, v241
	v_and_b32_e32 v244, 3, v244
	v_lshlrev_b32_e32 v236, 5, v244
	v_add_u32_e32 v244, 1, v241
	v_and_b32_e32 v244, 3, v244
	v_lshlrev_b32_e32 v237, 5, v244
	v_add_u32_e32 v244, 2, v241
	v_and_b32_e32 v244, 3, v244
	v_lshlrev_b32_e32 v238, 5, v244
	v_add_u32_e32 v244, 3, v241
	v_and_b32_e32 v244, 3, v244
	v_lshlrev_b32_e32 v239, 5, v244
	v_mul_u32_u24_e32 v243, 1, v241
	v_and_b32_e32 v243, 3, v243
	v_cmp_eq_u32_e64 s[12:13], 0, v243
	s_nop 3
	v_cndmask_b32_e64 v222, 0, 1.0, s[12:13]
	v_cmp_eq_u32_e64 s[12:13], 2, v243
	s_nop 3
	v_cndmask_b32_e64 v222, v222, -1.0, s[12:13]
	v_cmp_eq_u32_e64 s[12:13], 1, v243
	s_nop 3
	v_cndmask_b32_e64 v223, 0, -1.0, s[12:13]
	v_cmp_eq_u32_e64 s[12:13], 3, v243
	s_nop 3
	v_cndmask_b32_e64 v223, v223, 1.0, s[12:13]
	v_mul_u32_u24_e32 v243, 2, v241
	v_and_b32_e32 v243, 3, v243
	v_cmp_eq_u32_e64 s[12:13], 0, v243
	s_nop 3
	v_cndmask_b32_e64 v224, 0, 1.0, s[12:13]
	v_cmp_eq_u32_e64 s[12:13], 2, v243
	s_nop 3
	v_cndmask_b32_e64 v224, v224, -1.0, s[12:13]
	v_cmp_eq_u32_e64 s[12:13], 1, v243
	s_nop 3
	v_cndmask_b32_e64 v225, 0, -1.0, s[12:13]
	v_cmp_eq_u32_e64 s[12:13], 3, v243
	s_nop 3
	v_cndmask_b32_e64 v225, v225, 1.0, s[12:13]
	v_mul_u32_u24_e32 v243, 3, v241
	v_and_b32_e32 v243, 3, v243
	v_cmp_eq_u32_e64 s[12:13], 0, v243
	s_nop 3
	v_cndmask_b32_e64 v226, 0, 1.0, s[12:13]
	v_cmp_eq_u32_e64 s[12:13], 2, v243
	s_nop 3
	v_cndmask_b32_e64 v226, v226, -1.0, s[12:13]
	v_cmp_eq_u32_e64 s[12:13], 1, v243
	s_nop 3
	v_cndmask_b32_e64 v227, 0, -1.0, s[12:13]
	v_cmp_eq_u32_e64 s[12:13], 3, v243
	s_nop 3
	v_cndmask_b32_e64 v227, v227, 1.0, s[12:13]
	v_add_u32_e32 v242, 0, v241
	v_and_b32_e32 v242, 3, v242
	v_mov_b32_e32 v30, 1.0
	v_mov_b32_e32 v31, 0
	v_cmp_eq_u32_e64 s[12:13], 1, v242
	s_nop 3
	v_cndmask_b32_e64 v30, v30, v218, s[12:13]
	v_cndmask_b32_e64 v31, v31, v219, s[12:13]
	v_cmp_eq_u32_e64 s[12:13], 2, v242
	s_nop 3
	v_cndmask_b32_e64 v30, v30, v220, s[12:13]
	v_cndmask_b32_e64 v31, v31, v221, s[12:13]
	v_cmp_eq_u32_e64 s[12:13], 3, v242
	s_nop 3
	v_cndmask_b32_e64 v30, v30, v28, s[12:13]
	v_cndmask_b32_e64 v31, v31, v29, s[12:13]
	v_add_u32_e32 v243, 0, v241
	v_mul_u32_u24_e32 v243, v243, v241
	v_and_b32_e32 v243, 3, v243
	v_cmp_eq_u32_e64 s[12:13], 0, v243
	s_nop 3
	v_cndmask_b32_e64 v32, 0, 1.0, s[12:13]
	v_cmp_eq_u32_e64 s[12:13], 2, v243
	s_nop 3
	v_cndmask_b32_e64 v32, v32, -1.0, s[12:13]
	v_cmp_eq_u32_e64 s[12:13], 1, v243
	s_nop 3
	v_cndmask_b32_e64 v33, 0, -1.0, s[12:13]
	v_cmp_eq_u32_e64 s[12:13], 3, v243
	s_nop 3
	v_cndmask_b32_e64 v33, v33, 1.0, s[12:13]
	v_pk_mul_f32 v[34:35], v[30:31], v[32:33] op_sel:[1,1] op_sel_hi:[1,0]
	s_nop 0
	v_pk_fma_f32 v[228:229], v[30:31], v[32:33], v[34:35] op_sel_hi:[0,1,1] neg_lo:[0,0,1]
	s_nop 0
	v_add_u32_e32 v242, 1, v241
	v_and_b32_e32 v242, 3, v242
	v_mov_b32_e32 v30, 1.0
	v_mov_b32_e32 v31, 0
	v_cmp_eq_u32_e64 s[12:13], 1, v242
	s_nop 3
	v_cndmask_b32_e64 v30, v30, v218, s[12:13]
	v_cndmask_b32_e64 v31, v31, v219, s[12:13]
	v_cmp_eq_u32_e64 s[12:13], 2, v242
	s_nop 3
	v_cndmask_b32_e64 v30, v30, v220, s[12:13]
	v_cndmask_b32_e64 v31, v31, v221, s[12:13]
	v_cmp_eq_u32_e64 s[12:13], 3, v242
	s_nop 3
	v_cndmask_b32_e64 v30, v30, v28, s[12:13]
	v_cndmask_b32_e64 v31, v31, v29, s[12:13]
	v_add_u32_e32 v243, 1, v241
	v_mul_u32_u24_e32 v243, v243, v241
	v_and_b32_e32 v243, 3, v243
	v_cmp_eq_u32_e64 s[12:13], 0, v243
	s_nop 3
	v_cndmask_b32_e64 v32, 0, 1.0, s[12:13]
	v_cmp_eq_u32_e64 s[12:13], 2, v243
	s_nop 3
	v_cndmask_b32_e64 v32, v32, -1.0, s[12:13]
	v_cmp_eq_u32_e64 s[12:13], 1, v243
	s_nop 3
	v_cndmask_b32_e64 v33, 0, -1.0, s[12:13]
	v_cmp_eq_u32_e64 s[12:13], 3, v243
; DI float2 twid(float r) { return float2{__builtin_amdgcn_cosf(r), -__builtin_amdgcn_sinf(r)}; }
; DI void bfly_fwd(float2 a0, float2 a1, float2 a2, float2 a3, float r, float2& o0, float2& o1, float2& o2, float2& o3) {
;   float2 t0 = {a0.x + a2.x, a0.y + a2.y}, t1 = {a0.x - a2.x, a0.y - a2.y}, t2 = {a1.x + a3.x, a1.y + a3.y}, t3 = {a1.x - a3.x, a1.y - a3.y};
;   float2 b0 = {t0.x + t2.x, t0.y + t2.y}, b2 = {t0.x - t2.x, t0.y - t2.y}, b1 = {t1.x + t3.y, t1.y - t3.x}, b3 = {t1.x - t3.y, t1.y + t3.x};
;   float2 w1 = twid(r), w2 = cmul(w1, w1), w3 = cmul(w2, w1);
;   o0 = b0; o1 = cmul(b1, w1); o2 = cmul(b2, w2); o3 = cmul(b3, w3);
; }
;   const int Q = 1 << lq; const float invM = 1.f / (float)(4 << lq);
;   for (int bb = tid; bb < NBT * (N / 4); bb += NTHR) { const int b = bb & (N / 4 - 1); float2* z = z0 + (bb / (N / 4)) * N; int j = b & (Q - 1), base = ((b >> lq) << (lq + 2)) + j; float2 o0, o1, o2, o3;
;     bfly_fwd(z[base], z[base + Q], z[base + 2 * Q], z[base + 3 * Q], (float)j * invM, o0, o1, o2, o3);
;     z[base] = o0; z[base + Q] = o1; z[base + 2 * Q] = o2; z[base + 3 * Q] = o3; }
;   __syncthreads();
	s_nop 3
	v_cndmask_b32_e64 v33, v33, 1.0, s[12:13]
	v_pk_mul_f32 v[34:35], v[30:31], v[32:33] op_sel:[1,1] op_sel_hi:[1,0]
	s_nop 0
	v_pk_fma_f32 v[230:231], v[30:31], v[32:33], v[34:35] op_sel_hi:[0,1,1] neg_lo:[0,0,1]
	s_nop 0
	v_add_u32_e32 v242, 2, v241
	v_and_b32_e32 v242, 3, v242
	v_mov_b32_e32 v30, 1.0
	v_mov_b32_e32 v31, 0
	v_cmp_eq_u32_e64 s[12:13], 1, v242
	s_nop 3
	v_cndmask_b32_e64 v30, v30, v218, s[12:13]
	v_cndmask_b32_e64 v31, v31, v219, s[12:13]
	v_cmp_eq_u32_e64 s[12:13], 2, v242
	s_nop 3
	v_cndmask_b32_e64 v30, v30, v220, s[12:13]
	v_cndmask_b32_e64 v31, v31, v221, s[12:13]
	v_cmp_eq_u32_e64 s[12:13], 3, v242
	s_nop 3
	v_cndmask_b32_e64 v30, v30, v28, s[12:13]
	v_cndmask_b32_e64 v31, v31, v29, s[12:13]
	v_add_u32_e32 v243, 2, v241
	v_mul_u32_u24_e32 v243, v243, v241
	v_and_b32_e32 v243, 3, v243
	v_cmp_eq_u32_e64 s[12:13], 0, v243
	s_nop 3
	v_cndmask_b32_e64 v32, 0, 1.0, s[12:13]
	v_cmp_eq_u32_e64 s[12:13], 2, v243
	s_nop 3
	v_cndmask_b32_e64 v32, v32, -1.0, s[12:13]
	v_cmp_eq_u32_e64 s[12:13], 1, v243
	s_nop 3
	v_cndmask_b32_e64 v33, 0, -1.0, s[12:13]
	v_cmp_eq_u32_e64 s[12:13], 3, v243
	s_nop 3
	v_cndmask_b32_e64 v33, v33, 1.0, s[12:13]
	v_pk_mul_f32 v[34:35], v[30:31], v[32:33] op_sel:[1,1] op_sel_hi:[1,0]
	s_nop 0
	v_pk_fma_f32 v[232:233], v[30:31], v[32:33], v[34:35] op_sel_hi:[0,1,1] neg_lo:[0,0,1]
	s_nop 0
	v_add_u32_e32 v242, 3, v241
	v_and_b32_e32 v242, 3, v242
	v_mov_b32_e32 v30, 1.0
	v_mov_b32_e32 v31, 0
	v_cmp_eq_u32_e64 s[12:13], 1, v242
	s_nop 3
	v_cndmask_b32_e64 v30, v30, v218, s[12:13]
	v_cndmask_b32_e64 v31, v31, v219, s[12:13]
	v_cmp_eq_u32_e64 s[12:13], 2, v242
	s_nop 3
	v_cndmask_b32_e64 v30, v30, v220, s[12:13]
	v_cndmask_b32_e64 v31, v31, v221, s[12:13]
	v_cmp_eq_u32_e64 s[12:13], 3, v242
	s_nop 3
	v_cndmask_b32_e64 v30, v30, v28, s[12:13]
	v_cndmask_b32_e64 v31, v31, v29, s[12:13]
	v_add_u32_e32 v243, 3, v241
	v_mul_u32_u24_e32 v243, v243, v241
	v_and_b32_e32 v243, 3, v243
	v_cmp_eq_u32_e64 s[12:13], 0, v243
	s_nop 3
	v_cndmask_b32_e64 v32, 0, 1.0, s[12:13]
	v_cmp_eq_u32_e64 s[12:13], 2, v243
	s_nop 3
	v_cndmask_b32_e64 v32, v32, -1.0, s[12:13]
	v_cmp_eq_u32_e64 s[12:13], 1, v243
	s_nop 3
	v_cndmask_b32_e64 v33, 0, -1.0, s[12:13]
	v_cmp_eq_u32_e64 s[12:13], 3, v243
	s_nop 3
	v_cndmask_b32_e64 v33, v33, 1.0, s[12:13]
	v_pk_mul_f32 v[34:35], v[30:31], v[32:33] op_sel:[1,1] op_sel_hi:[1,0]
	s_nop 0
	v_pk_fma_f32 v[234:235], v[30:31], v[32:33], v[34:35] op_sel_hi:[0,1,1] neg_lo:[0,0,1]
	s_nop 0
.LBB0_1606:
	v_ashrrev_i32_e32 v19, 31, v18
	v_lshrrev_b32_e32 v19, 21, v19
	v_add_lshl_u32 v19, v18, v19, 5
	v_and_b32_e32 v19, 0xffff0000, v19
	v_and_b32_e32 v20, 0x1ff0, v17
	v_add_u32_e32 v19, 16, v19
	v_lshlrev_b32_e32 v20, 3, v20
	v_lshlrev_b32_e32 v21, 3, v14
	v_add3_u32 v19, v19, v20, v21
	v_add_u32_e32 v241, v19, v236
	v_add_u32_e32 v242, v19, v237
	v_add_u32_e32 v243, v19, v238
	v_add_u32_e32 v244, v19, v239
	ds_read_b64 v[20:21], v241
	ds_read_b64 v[22:23], v242
	ds_read_b64 v[24:25], v243
	ds_read_b64 v[26:27], v244
	v_cmp_lt_i32_e64 s[12:13], s25, v18
	v_add_u32_e32 v17, 0x800, v17
	s_or_b64 s[80:81], s[12:13], s[80:81]
	s_waitcnt lgkmcnt(0)
	v_pk_mul_f32 v[218:219], v[22:23], v[222:223] op_sel:[1,1] op_sel_hi:[1,0]
	v_pk_mul_f32 v[220:221], v[24:25], v[224:225] op_sel:[1,1] op_sel_hi:[1,0]
	v_pk_mul_f32 v[28:29], v[26:27], v[226:227] op_sel:[1,1] op_sel_hi:[1,0]
	v_pk_fma_f32 v[22:23], v[22:23], v[222:223], v[218:219] op_sel_hi:[0,1,1] neg_lo:[0,0,1]
	v_pk_fma_f32 v[24:25], v[24:25], v[224:225], v[220:221] op_sel_hi:[0,1,1] neg_lo:[0,0,1]
	v_pk_fma_f32 v[26:27], v[26:27], v[226:227], v[28:29] op_sel_hi:[0,1,1] neg_lo:[0,0,1]
	v_pk_add_f32 v[28:29], v[20:21], v[24:25]
	v_pk_add_f32 v[30:31], v[20:21], v[24:25] neg_lo:[0,1] neg_hi:[0,1]
	v_pk_add_f32 v[32:33], v[22:23], v[26:27]
	v_pk_add_f32 v[34:35], v[22:23], v[26:27] neg_lo:[0,1] neg_hi:[0,1]
	v_pk_add_f32 v[20:21], v[28:29], v[32:33]
	v_pk_add_f32 v[24:25], v[28:29], v[32:33] neg_lo:[0,1] neg_hi:[0,1]
	v_pk_add_f32 v[22:23], v[30:31], v[34:35] op_sel:[0,1] op_sel_hi:[1,0] neg_hi:[0,1]
	v_pk_add_f32 v[26:27], v[30:31], v[34:35] op_sel:[0,1] op_sel_hi:[1,0] neg_lo:[0,1]
	v_pk_mul_f32 v[218:219], v[20:21], v[228:229] op_sel:[1,1] op_sel_hi:[1,0]
	v_pk_mul_f32 v[220:221], v[24:25], v[232:233] op_sel:[1,1] op_sel_hi:[1,0]
	v_pk_mul_f32 v[28:29], v[22:23], v[230:231] op_sel:[1,1] op_sel_hi:[1,0]
	v_pk_mul_f32 v[32:33], v[26:27], v[234:235] op_sel:[1,1] op_sel_hi:[1,0]
	v_pk_fma_f32 v[20:21], v[20:21], v[228:229], v[218:219] op_sel_hi:[0,1,1] neg_lo:[0,0,1]
	v_pk_fma_f32 v[24:25], v[24:25], v[232:233], v[220:221] op_sel_hi:[0,1,1] neg_lo:[0,0,1]
	v_pk_fma_f32 v[22:23], v[22:23], v[230:231], v[28:29] op_sel_hi:[0,1,1] neg_lo:[0,0,1]
	v_pk_fma_f32 v[26:27], v[26:27], v[234:235], v[32:33] op_sel_hi:[0,1,1] neg_lo:[0,0,1]
	s_nop 0
	ds_write_b64 v241, v[20:21]
	ds_write_b64 v243, v[24:25]
	ds_write_b64 v242, v[22:23]
	ds_write_b64 v244, v[26:27]
	v_add_u32_e32 v19, 0x200, v18
	v_mov_b32_e32 v18, v19
	s_andn2_b64 exec, exec, s[80:81]
	s_cbranch_execnz .LBB0_1606

; DI float2 twid(float r) { return float2{__builtin_amdgcn_cosf(r), -__builtin_amdgcn_sinf(r)}; }
; DI void bfly_inv(float2 s0, float2 s1, float2 s2, float2 s3, float r, float2& o0, float2& o1, float2& o2, float2& o3) {
;   float2 w1 = twid(r), w2 = cmul(w1, w1), w3 = cmul(w2, w1);
;   float2 c0 = s0, c1 = cmulc(s1, w1), c2 = cmulc(s2, w2), c3 = cmulc(s3, w3);
;   float2 t0 = {c0.x + c2.x, c0.y + c2.y}, t1 = {c0.x - c2.x, c0.y - c2.y}, t2 = {c1.x + c3.x, c1.y + c3.y}, t3 = {c1.x - c3.x, c1.y - c3.y};
;   o0 = float2{t0.x + t2.x, t0.y + t2.y}; o2 = float2{t0.x - t2.x, t0.y - t2.y}; o1 = float2{t1.x - t3.y, t1.y + t3.x}; o3 = float2{t1.x + t3.y, t1.y - t3.x};
; }
;   const int Q = 1 << lq; const float invM = 1.f / (float)(4 << lq);
;   for (int bb = tid; bb < NBT * (N / 4); bb += NTHR) { const int b = bb & (N / 4 - 1); float2* z = z0 + (bb / (N / 4)) * N; int j = b & (Q - 1), base = ((b >> lq) << (lq + 2)) + j; float2 o0, o1, o2, o3;
;     bfly_inv(z[base], z[base + Q], z[base + 2 * Q], z[base + 3 * Q], (float)j * invM, o0, o1, o2, o3);
;     z[base] = o0; z[base + Q] = o1; z[base + 2 * Q] = o2; z[base + 3 * Q] = o3; }
;   __syncthreads();
.LBB0_1613:
	s_or_b64 exec, exec, s[0:1]
	s_waitcnt lgkmcnt(0)
	s_barrier
	s_and_saveexec_b64 s[0:1], s[10:11]
	s_cbranch_execz .LBB0_1616
	v_mul_f32_e32 v2, 0x3d800000, v16
	v_sin_f32_e32 v3, v2
	v_cos_f32_e32 v5, v2
	s_mov_b64 s[80:81], 0
	v_mov_b32_e32 v16, v75
	v_mul_f32_e32 v2, v3, v3
	v_mul_f32_e64 v4, v5, -v3
	v_fma_f32 v6, v5, v5, -v2
	v_add_f32_e32 v8, v4, v4
	v_mul_f32_e32 v2, v3, v8
	v_mul_f32_e32 v4, v3, v6
	v_fmac_f32_e32 v2, v5, v6
	v_fma_f32 v4, v5, v8, -v4
	v_mov_b32_e32 v7, v6
	v_pk_mov_b32 v[10:11], v[4:5], v[2:3] op_sel:[1,0]
	v_pk_mov_b32 v[12:13], v[2:3], v[4:5] op_sel:[1,0]
	v_mov_b32_e32 v9, v8
	v_and_b32_e32 v248, 3, v16
	v_cvt_f32_u32_e32 v248, v248
	v_mul_f32_e32 v248, 0x3d800000, v248
	v_cos_f32_e32 v220, v248
	v_sin_f32_e32 v221, v248
	s_nop 1
	v_xor_b32_e32 v221, 0x80000000, v221
	s_nop 0
	v_pk_mul_f32 v[218:219], v[220:221], v[220:221] op_sel:[1,1] op_sel_hi:[1,0]
	s_nop 0
	v_pk_fma_f32 v[222:223], v[220:221], v[220:221], v[218:219] op_sel_hi:[0,1,1] neg_lo:[0,0,1]
	s_nop 0
	v_pk_mul_f32 v[218:219], v[222:223], v[220:221] op_sel:[1,1] op_sel_hi:[1,0]
	s_nop 0
	v_pk_fma_f32 v[26:27], v[222:223], v[220:221], v[218:219] op_sel_hi:[0,1,1] neg_lo:[0,0,1]
	s_nop 0
	v_bfe_u32 v245, v16, 2, 2
	v_bfe_u32 v248, v16, 4, 1
	v_add_u32_e32 v245, v245, v248
	v_and_b32_e32 v245, 3, v245
	v_add_u32_e32 v248, 0, v245
	v_and_b32_e32 v248, 3, v248
	v_lshlrev_b32_e32 v241, 5, v248
	v_add_u32_e32 v248, 1, v245
	v_and_b32_e32 v248, 3, v248
	v_lshlrev_b32_e32 v242, 5, v248
	v_add_u32_e32 v248, 2, v245
	v_and_b32_e32 v248, 3, v248
	v_lshlrev_b32_e32 v243, 5, v248
	v_add_u32_e32 v248, 3, v245
	v_and_b32_e32 v248, 3, v248
	v_lshlrev_b32_e32 v244, 5, v248
	v_add_u32_e32 v246, 0, v245
	v_and_b32_e32 v246, 3, v246
	v_mov_b32_e32 v28, 1.0
	v_mov_b32_e32 v29, 0
	v_cmp_eq_u32_e64 s[12:13], 1, v246
	s_nop 3
	v_cndmask_b32_e64 v28, v28, v220, s[12:13]
	v_cndmask_b32_e64 v29, v29, v221, s[12:13]
	v_cmp_eq_u32_e64 s[12:13], 2, v246
	s_nop 3
	v_cndmask_b32_e64 v28, v28, v222, s[12:13]
	v_cndmask_b32_e64 v29, v29, v223, s[12:13]
	v_cmp_eq_u32_e64 s[12:13], 3, v246
	s_nop 3
	v_cndmask_b32_e64 v28, v28, v26, s[12:13]
	v_cndmask_b32_e64 v29, v29, v27, s[12:13]
	v_xor_b32_e32 v29, 0x80000000, v29
	v_mul_u32_u24_e32 v247, 0, v245
	v_and_b32_e32 v247, 3, v247
	v_cmp_eq_u32_e64 s[12:13], 0, v247
	s_nop 3
	v_cndmask_b32_e64 v30, 0, 1.0, s[12:13]
	v_cmp_eq_u32_e64 s[12:13], 2, v247
	s_nop 3
	v_cndmask_b32_e64 v30, v30, -1.0, s[12:13]
	v_cmp_eq_u32_e64 s[12:13], 1, v247
	s_nop 3
	v_cndmask_b32_e64 v31, 0, 1.0, s[12:13]
	v_cmp_eq_u32_e64 s[12:13], 3, v247
	s_nop 3
	v_cndmask_b32_e64 v31, v31, -1.0, s[12:13]
	v_pk_mul_f32 v[218:219], v[28:29], v[30:31] op_sel:[1,1] op_sel_hi:[1,0]
	s_nop 0
	v_pk_fma_f32 v[224:225], v[28:29], v[30:31], v[218:219] op_sel_hi:[0,1,1] neg_lo:[0,0,1]
	s_nop 0
	v_add_u32_e32 v246, 1, v245
	v_and_b32_e32 v246, 3, v246
	v_mov_b32_e32 v28, 1.0
	v_mov_b32_e32 v29, 0
	v_cmp_eq_u32_e64 s[12:13], 1, v246
	s_nop 3
	v_cndmask_b32_e64 v28, v28, v220, s[12:13]
	v_cndmask_b32_e64 v29, v29, v221, s[12:13]
	v_cmp_eq_u32_e64 s[12:13], 2, v246
	s_nop 3
	v_cndmask_b32_e64 v28, v28, v222, s[12:13]
	v_cndmask_b32_e64 v29, v29, v223, s[12:13]
	v_cmp_eq_u32_e64 s[12:13], 3, v246
	s_nop 3
	v_cndmask_b32_e64 v28, v28, v26, s[12:13]
	v_cndmask_b32_e64 v29, v29, v27, s[12:13]
	v_xor_b32_e32 v29, 0x80000000, v29
	v_mul_u32_u24_e32 v247, 1, v245
	v_and_b32_e32 v247, 3, v247
	v_cmp_eq_u32_e64 s[12:13], 0, v247
	s_nop 3
	v_cndmask_b32_e64 v30, 0, 1.0, s[12:13]
	v_cmp_eq_u32_e64 s[12:13], 2, v247
	s_nop 3
	v_cndmask_b32_e64 v30, v30, -1.0, s[12:13]
	v_cmp_eq_u32_e64 s[12:13], 1, v247
	s_nop 3
	v_cndmask_b32_e64 v31, 0, 1.0, s[12:13]
	v_cmp_eq_u32_e64 s[12:13], 3, v247
	s_nop 3
	v_cndmask_b32_e64 v31, v31, -1.0, s[12:13]
	v_pk_mul_f32 v[218:219], v[28:29], v[30:31] op_sel:[1,1] op_sel_hi:[1,0]
	s_nop 0
	v_pk_fma_f32 v[226:227], v[28:29], v[30:31], v[218:219] op_sel_hi:[0,1,1] neg_lo:[0,0,1]
	s_nop 0
	v_add_u32_e32 v246, 2, v245
	v_and_b32_e32 v246, 3, v246
	v_mov_b32_e32 v28, 1.0
	v_mov_b32_e32 v29, 0
	v_cmp_eq_u32_e64 s[12:13], 1, v246
	s_nop 3
	v_cndmask_b32_e64 v28, v28, v220, s[12:13]
	v_cndmask_b32_e64 v29, v29, v221, s[12:13]
	v_cmp_eq_u32_e64 s[12:13], 2, v246
	s_nop 3
	v_cndmask_b32_e64 v28, v28, v222, s[12:13]
	v_cndmask_b32_e64 v29, v29, v223, s[12:13]
	v_cmp_eq_u32_e64 s[12:13], 3, v246
	s_nop 3
	v_cndmask_b32_e64 v28, v28, v26, s[12:13]
	v_cndmask_b32_e64 v29, v29, v27, s[12:13]
	v_xor_b32_e32 v29, 0x80000000, v29
	v_mul_u32_u24_e32 v247, 2, v245
	v_and_b32_e32 v247, 3, v247
	v_cmp_eq_u32_e64 s[12:13], 0, v247
	s_nop 3
	v_cndmask_b32_e64 v30, 0, 1.0, s[12:13]
	v_cmp_eq_u32_e64 s[12:13], 2, v247
	s_nop 3
	v_cndmask_b32_e64 v30, v30, -1.0, s[12:13]
	v_cmp_eq_u32_e64 s[12:13], 1, v247
	s_nop 3
	v_cndmask_b32_e64 v31, 0, 1.0, s[12:13]
	v_cmp_eq_u32_e64 s[12:13], 3, v247
	s_nop 3
	v_cndmask_b32_e64 v31, v31, -1.0, s[12:13]
	v_pk_mul_f32 v[218:219], v[28:29], v[30:31] op_sel:[1,1] op_sel_hi:[1,0]
	s_nop 0
	v_pk_fma_f32 v[228:229], v[28:29], v[30:31], v[218:219] op_sel_hi:[0,1,1] neg_lo:[0,0,1]
	s_nop 0
	v_add_u32_e32 v246, 3, v245
	v_and_b32_e32 v246, 3, v246
	v_mov_b32_e32 v28, 1.0
	v_mov_b32_e32 v29, 0
	v_cmp_eq_u32_e64 s[12:13], 1, v246
	s_nop 3
	v_cndmask_b32_e64 v28, v28, v220, s[12:13]
	v_cndmask_b32_e64 v29, v29, v221, s[12:13]
	v_cmp_eq_u32_e64 s[12:13], 2, v246
	s_nop 3
; DI float2 twid(float r) { return float2{__builtin_amdgcn_cosf(r), -__builtin_amdgcn_sinf(r)}; }
; DI void bfly_inv(float2 s0, float2 s1, float2 s2, float2 s3, float r, float2& o0, float2& o1, float2& o2, float2& o3) {
;   float2 w1 = twid(r), w2 = cmul(w1, w1), w3 = cmul(w2, w1);
;   float2 c0 = s0, c1 = cmulc(s1, w1), c2 = cmulc(s2, w2), c3 = cmulc(s3, w3);
;   float2 t0 = {c0.x + c2.x, c0.y + c2.y}, t1 = {c0.x - c2.x, c0.y - c2.y}, t2 = {c1.x + c3.x, c1.y + c3.y}, t3 = {c1.x - c3.x, c1.y - c3.y};
;   o0 = float2{t0.x + t2.x, t0.y + t2.y}; o2 = float2{t0.x - t2.x, t0.y - t2.y}; o1 = float2{t1.x - t3.y, t1.y + t3.x}; o3 = float2{t1.x + t3.y, t1.y - t3.x};
; }
;   const int Q = 1 << lq; const float invM = 1.f / (float)(4 << lq);
;   for (int bb = tid; bb < NBT * (N / 4); bb += NTHR) { const int b = bb & (N / 4 - 1); float2* z = z0 + (bb / (N / 4)) * N; int j = b & (Q - 1), base = ((b >> lq) << (lq + 2)) + j; float2 o0, o1, o2, o3;
;     bfly_inv(z[base], z[base + Q], z[base + 2 * Q], z[base + 3 * Q], (float)j * invM, o0, o1, o2, o3);
;     z[base] = o0; z[base + Q] = o1; z[base + 2 * Q] = o2; z[base + 3 * Q] = o3; }
;   __syncthreads();
	v_cndmask_b32_e64 v28, v28, v222, s[12:13]
	v_cndmask_b32_e64 v29, v29, v223, s[12:13]
	v_cmp_eq_u32_e64 s[12:13], 3, v246
	s_nop 3
	v_cndmask_b32_e64 v28, v28, v26, s[12:13]
	v_cndmask_b32_e64 v29, v29, v27, s[12:13]
	v_xor_b32_e32 v29, 0x80000000, v29
	v_mul_u32_u24_e32 v247, 3, v245
	v_and_b32_e32 v247, 3, v247
	v_cmp_eq_u32_e64 s[12:13], 0, v247
	s_nop 3
	v_cndmask_b32_e64 v30, 0, 1.0, s[12:13]
	v_cmp_eq_u32_e64 s[12:13], 2, v247
	s_nop 3
	v_cndmask_b32_e64 v30, v30, -1.0, s[12:13]
	v_cmp_eq_u32_e64 s[12:13], 1, v247
	s_nop 3
	v_cndmask_b32_e64 v31, 0, 1.0, s[12:13]
	v_cmp_eq_u32_e64 s[12:13], 3, v247
	s_nop 3
	v_cndmask_b32_e64 v31, v31, -1.0, s[12:13]
	v_pk_mul_f32 v[218:219], v[28:29], v[30:31] op_sel:[1,1] op_sel_hi:[1,0]
	s_nop 0
	v_pk_fma_f32 v[230:231], v[28:29], v[30:31], v[218:219] op_sel_hi:[0,1,1] neg_lo:[0,0,1]
	s_nop 0
	v_add_u32_e32 v247, 0, v245
	v_mul_u32_u24_e32 v247, v247, v245
	v_and_b32_e32 v247, 3, v247
	v_cmp_eq_u32_e64 s[12:13], 0, v247
	s_nop 3
	v_cndmask_b32_e64 v232, 0, 1.0, s[12:13]
	v_cmp_eq_u32_e64 s[12:13], 2, v247
	s_nop 3
	v_cndmask_b32_e64 v232, v232, -1.0, s[12:13]
	v_cmp_eq_u32_e64 s[12:13], 1, v247
	s_nop 3
	v_cndmask_b32_e64 v233, 0, 1.0, s[12:13]
	v_cmp_eq_u32_e64 s[12:13], 3, v247
	s_nop 3
	v_cndmask_b32_e64 v233, v233, -1.0, s[12:13]
	v_add_u32_e32 v247, 1, v245
	v_mul_u32_u24_e32 v247, v247, v245
	v_and_b32_e32 v247, 3, v247
	v_cmp_eq_u32_e64 s[12:13], 0, v247
	s_nop 3
	v_cndmask_b32_e64 v234, 0, 1.0, s[12:13]
	v_cmp_eq_u32_e64 s[12:13], 2, v247
	s_nop 3
	v_cndmask_b32_e64 v234, v234, -1.0, s[12:13]
	v_cmp_eq_u32_e64 s[12:13], 1, v247
	s_nop 3
	v_cndmask_b32_e64 v235, 0, 1.0, s[12:13]
	v_cmp_eq_u32_e64 s[12:13], 3, v247
	s_nop 3
	v_cndmask_b32_e64 v235, v235, -1.0, s[12:13]
	v_add_u32_e32 v247, 2, v245
	v_mul_u32_u24_e32 v247, v247, v245
	v_and_b32_e32 v247, 3, v247
	v_cmp_eq_u32_e64 s[12:13], 0, v247
	s_nop 3
	v_cndmask_b32_e64 v236, 0, 1.0, s[12:13]
	v_cmp_eq_u32_e64 s[12:13], 2, v247
	s_nop 3
	v_cndmask_b32_e64 v236, v236, -1.0, s[12:13]
	v_cmp_eq_u32_e64 s[12:13], 1, v247
	s_nop 3
	v_cndmask_b32_e64 v237, 0, 1.0, s[12:13]
	v_cmp_eq_u32_e64 s[12:13], 3, v247
	s_nop 3
	v_cndmask_b32_e64 v237, v237, -1.0, s[12:13]
	v_add_u32_e32 v247, 3, v245
	v_mul_u32_u24_e32 v247, v247, v245
	v_and_b32_e32 v247, 3, v247
	v_cmp_eq_u32_e64 s[12:13], 0, v247
	s_nop 3
	v_cndmask_b32_e64 v238, 0, 1.0, s[12:13]
	v_cmp_eq_u32_e64 s[12:13], 2, v247
	s_nop 3
	v_cndmask_b32_e64 v238, v238, -1.0, s[12:13]
	v_cmp_eq_u32_e64 s[12:13], 1, v247
	s_nop 3
	v_cndmask_b32_e64 v239, 0, 1.0, s[12:13]
	v_cmp_eq_u32_e64 s[12:13], 3, v247
	s_nop 3
	v_cndmask_b32_e64 v239, v239, -1.0, s[12:13]
.LBB0_1615:
	v_ashrrev_i32_e32 v17, 31, v16
	v_lshrrev_b32_e32 v17, 21, v17
	v_add_lshl_u32 v17, v16, v17, 5
	v_and_b32_e32 v17, 0xffff0000, v17
	v_and_b32_e32 v18, 0x1ff0, v15
	v_add_u32_e32 v17, 16, v17
	v_lshlrev_b32_e32 v18, 3, v18
	v_lshlrev_b32_e32 v19, 3, v14
	v_add3_u32 v17, v17, v18, v19
	v_add_u32_e32 v245, v17, v241
	v_add_u32_e32 v246, v17, v242
	v_add_u32_e32 v247, v17, v243
	v_add_u32_e32 v248, v17, v244
	ds_read_b64 v[18:19], v245
	ds_read_b64 v[20:21], v246
	ds_read_b64 v[22:23], v247
	ds_read_b64 v[24:25], v248
	v_cmp_lt_i32_e64 s[12:13], s25, v16
	v_add_u32_e32 v15, 0x800, v15
	s_or_b64 s[80:81], s[12:13], s[80:81]
	s_waitcnt lgkmcnt(0)
	v_pk_mul_f32 v[220:221], v[18:19], v[224:225] op_sel:[1,1] op_sel_hi:[1,0]
	v_pk_mul_f32 v[222:223], v[20:21], v[226:227] op_sel:[1,1] op_sel_hi:[1,0]
	v_pk_mul_f32 v[26:27], v[22:23], v[228:229] op_sel:[1,1] op_sel_hi:[1,0]
	v_pk_mul_f32 v[28:29], v[24:25], v[230:231] op_sel:[1,1] op_sel_hi:[1,0]
	v_pk_fma_f32 v[18:19], v[18:19], v[224:225], v[220:221] op_sel_hi:[0,1,1] neg_lo:[0,0,1]
	v_pk_fma_f32 v[20:21], v[20:21], v[226:227], v[222:223] op_sel_hi:[0,1,1] neg_lo:[0,0,1]
	v_pk_fma_f32 v[22:23], v[22:23], v[228:229], v[26:27] op_sel_hi:[0,1,1] neg_lo:[0,0,1]
	v_pk_fma_f32 v[24:25], v[24:25], v[230:231], v[28:29] op_sel_hi:[0,1,1] neg_lo:[0,0,1]
	v_pk_add_f32 v[26:27], v[18:19], v[22:23]
	v_pk_add_f32 v[28:29], v[18:19], v[22:23] neg_lo:[0,1] neg_hi:[0,1]
	v_pk_add_f32 v[30:31], v[20:21], v[24:25]
	v_pk_add_f32 v[218:219], v[20:21], v[24:25] neg_lo:[0,1] neg_hi:[0,1]
	v_pk_add_f32 v[18:19], v[26:27], v[30:31]
	v_pk_add_f32 v[22:23], v[26:27], v[30:31] neg_lo:[0,1] neg_hi:[0,1]
	v_pk_add_f32 v[20:21], v[28:29], v[218:219] op_sel:[0,1] op_sel_hi:[1,0] neg_lo:[0,1]
	v_pk_add_f32 v[24:25], v[28:29], v[218:219] op_sel:[0,1] op_sel_hi:[1,0] neg_hi:[0,1]
	v_pk_mul_f32 v[220:221], v[18:19], v[232:233] op_sel:[1,1] op_sel_hi:[1,0]
	v_pk_mul_f32 v[222:223], v[22:23], v[236:237] op_sel:[1,1] op_sel_hi:[1,0]
	v_pk_mul_f32 v[26:27], v[20:21], v[234:235] op_sel:[1,1] op_sel_hi:[1,0]
	v_pk_mul_f32 v[30:31], v[24:25], v[238:239] op_sel:[1,1] op_sel_hi:[1,0]
	v_pk_fma_f32 v[18:19], v[18:19], v[232:233], v[220:221] op_sel_hi:[0,1,1] neg_lo:[0,0,1]
	v_pk_fma_f32 v[22:23], v[22:23], v[236:237], v[222:223] op_sel_hi:[0,1,1] neg_lo:[0,0,1]
	v_pk_fma_f32 v[20:21], v[20:21], v[234:235], v[26:27] op_sel_hi:[0,1,1] neg_lo:[0,0,1]
	v_pk_fma_f32 v[24:25], v[24:25], v[238:239], v[30:31] op_sel_hi:[0,1,1] neg_lo:[0,0,1]
	s_nop 0
	ds_write_b64 v245, v[18:19]
	ds_write_b64 v247, v[22:23]
	ds_write_b64 v246, v[20:21]
	ds_write_b64 v248, v[24:25]
	v_add_u32_e32 v17, 0x200, v16
	v_mov_b32_e32 v16, v17
	s_andn2_b64 exec, exec, s[80:81]
	s_cbranch_execnz .LBB0_1615

; DI float2 twid(float r) { return float2{__builtin_amdgcn_cosf(r), -__builtin_amdgcn_sinf(r)}; }
; DI void bfly_fwd(float2 a0, float2 a1, float2 a2, float2 a3, float r, float2& o0, float2& o1, float2& o2, float2& o3) {
;   float2 t0 = {a0.x + a2.x, a0.y + a2.y}, t1 = {a0.x - a2.x, a0.y - a2.y}, t2 = {a1.x + a3.x, a1.y + a3.y}, t3 = {a1.x - a3.x, a1.y - a3.y};
;   float2 b0 = {t0.x + t2.x, t0.y + t2.y}, b2 = {t0.x - t2.x, t0.y - t2.y}, b1 = {t1.x + t3.y, t1.y - t3.x}, b3 = {t1.x - t3.y, t1.y + t3.x};
;   float2 w1 = twid(r), w2 = cmul(w1, w1), w3 = cmul(w2, w1);
;   o0 = b0; o1 = cmul(b1, w1); o2 = cmul(b2, w2); o3 = cmul(b3, w3);
; }
;   const int Q = 1 << lq; const float invM = 1.f / (float)(4 << lq);
;   for (int bb = tid; bb < NBT * (N / 4); bb += NTHR) { const int b = bb & (N / 4 - 1); float2* z = z0 + (bb / (N / 4)) * N; int j = b & (Q - 1), base = ((b >> lq) << (lq + 2)) + j; float2 o0, o1, o2, o3;
;     bfly_fwd(z[base], z[base + Q], z[base + 2 * Q], z[base + 3 * Q], (float)j * invM, o0, o1, o2, o3);
;     z[base] = o0; z[base + Q] = o1; z[base + 2 * Q] = o2; z[base + 3 * Q] = o3; }
;   __syncthreads();
.LBB0_1636:
	s_or_b64 exec, exec, s[0:1]
	s_movk_i32 s0, 0x1000
	v_and_b32_e32 v16, 3, v76
	v_cmp_gt_i32_e64 s[12:13], s0, v76
	v_cvt_f32_ubyte0_e32 v18, v16
	v_lshlrev_b32_e32 v17, 2, v76
	s_waitcnt lgkmcnt(0)
	s_barrier
	s_and_saveexec_b64 s[0:1], s[12:13]
	s_cbranch_execz .LBB0_1639
	v_mul_f32_e32 v5, 0x3d800000, v18
	v_sin_f32_e32 v4, v5
	v_cos_f32_e32 v6, v5
	v_lshlrev_b32_e32 v19, 2, v76
	s_mov_b64 s[80:81], 0
	v_mul_f32_e32 v5, v4, v4
	v_mul_f32_e64 v7, v6, -v4
	v_fma_f32 v8, v6, v6, -v5
	v_add_f32_e32 v10, v7, v7
	v_mul_f32_e32 v12, v4, v10
	v_mul_f32_e32 v5, v4, v8
	v_fmac_f32_e32 v12, v6, v8
	v_fma_f32 v14, v6, v10, -v5
	v_mov_b32_e32 v7, v6
	v_mov_b32_e32 v5, v4
	v_mov_b32_e32 v9, v8
	v_mov_b32_e32 v13, v12
	v_mov_b32_e32 v15, v14
	v_mov_b32_e32 v11, v10
	v_mov_b32_e32 v20, v76
	v_and_b32_e32 v244, 3, v20
	v_cvt_f32_u32_e32 v244, v244
	v_mul_f32_e32 v244, 0x3d800000, v244
	v_cos_f32_e32 v218, v244
	v_sin_f32_e32 v219, v244
	s_nop 1
	v_xor_b32_e32 v219, 0x80000000, v219
	s_nop 0
	v_pk_mul_f32 v[36:37], v[218:219], v[218:219] op_sel:[1,1] op_sel_hi:[1,0]
	s_nop 0
	v_pk_fma_f32 v[220:221], v[218:219], v[218:219], v[36:37] op_sel_hi:[0,1,1] neg_lo:[0,0,1]
	s_nop 0
	v_pk_mul_f32 v[36:37], v[220:221], v[218:219] op_sel:[1,1] op_sel_hi:[1,0]
	s_nop 0
	v_pk_fma_f32 v[30:31], v[220:221], v[218:219], v[36:37] op_sel_hi:[0,1,1] neg_lo:[0,0,1]
	s_nop 0
	v_bfe_u32 v241, v20, 2, 2
	v_bfe_u32 v244, v20, 4, 1
	v_add_u32_e32 v241, v241, v244
	v_and_b32_e32 v241, 3, v241
	v_add_u32_e32 v244, 0, v241
	v_and_b32_e32 v244, 3, v244
	v_lshlrev_b32_e32 v236, 5, v244
	v_add_u32_e32 v244, 1, v241
	v_and_b32_e32 v244, 3, v244
	v_lshlrev_b32_e32 v237, 5, v244
	v_add_u32_e32 v244, 2, v241
	v_and_b32_e32 v244, 3, v244
	v_lshlrev_b32_e32 v238, 5, v244
	v_add_u32_e32 v244, 3, v241
	v_and_b32_e32 v244, 3, v244
	v_lshlrev_b32_e32 v239, 5, v244
	v_mul_u32_u24_e32 v243, 1, v241
	v_and_b32_e32 v243, 3, v243
	v_cmp_eq_u32_e64 s[14:15], 0, v243
	s_nop 3
	v_cndmask_b32_e64 v222, 0, 1.0, s[14:15]
	v_cmp_eq_u32_e64 s[14:15], 2, v243
	s_nop 3
	v_cndmask_b32_e64 v222, v222, -1.0, s[14:15]
	v_cmp_eq_u32_e64 s[14:15], 1, v243
	s_nop 3
	v_cndmask_b32_e64 v223, 0, -1.0, s[14:15]
	v_cmp_eq_u32_e64 s[14:15], 3, v243
	s_nop 3
	v_cndmask_b32_e64 v223, v223, 1.0, s[14:15]
	v_mul_u32_u24_e32 v243, 2, v241
	v_and_b32_e32 v243, 3, v243
	v_cmp_eq_u32_e64 s[14:15], 0, v243
	s_nop 3
	v_cndmask_b32_e64 v224, 0, 1.0, s[14:15]
	v_cmp_eq_u32_e64 s[14:15], 2, v243
	s_nop 3
	v_cndmask_b32_e64 v224, v224, -1.0, s[14:15]
	v_cmp_eq_u32_e64 s[14:15], 1, v243
	s_nop 3
	v_cndmask_b32_e64 v225, 0, -1.0, s[14:15]
	v_cmp_eq_u32_e64 s[14:15], 3, v243
	s_nop 3
	v_cndmask_b32_e64 v225, v225, 1.0, s[14:15]
	v_mul_u32_u24_e32 v243, 3, v241
	v_and_b32_e32 v243, 3, v243
	v_cmp_eq_u32_e64 s[14:15], 0, v243
	s_nop 3
	v_cndmask_b32_e64 v226, 0, 1.0, s[14:15]
	v_cmp_eq_u32_e64 s[14:15], 2, v243
	s_nop 3
	v_cndmask_b32_e64 v226, v226, -1.0, s[14:15]
	v_cmp_eq_u32_e64 s[14:15], 1, v243
	s_nop 3
	v_cndmask_b32_e64 v227, 0, -1.0, s[14:15]
	v_cmp_eq_u32_e64 s[14:15], 3, v243
	s_nop 3
	v_cndmask_b32_e64 v227, v227, 1.0, s[14:15]
	v_add_u32_e32 v242, 0, v241
	v_and_b32_e32 v242, 3, v242
	v_mov_b32_e32 v32, 1.0
	v_mov_b32_e32 v33, 0
	v_cmp_eq_u32_e64 s[14:15], 1, v242
	s_nop 3
	v_cndmask_b32_e64 v32, v32, v218, s[14:15]
	v_cndmask_b32_e64 v33, v33, v219, s[14:15]
	v_cmp_eq_u32_e64 s[14:15], 2, v242
	s_nop 3
	v_cndmask_b32_e64 v32, v32, v220, s[14:15]
	v_cndmask_b32_e64 v33, v33, v221, s[14:15]
	v_cmp_eq_u32_e64 s[14:15], 3, v242
	s_nop 3
	v_cndmask_b32_e64 v32, v32, v30, s[14:15]
	v_cndmask_b32_e64 v33, v33, v31, s[14:15]
	v_add_u32_e32 v243, 0, v241
	v_mul_u32_u24_e32 v243, v243, v241
	v_and_b32_e32 v243, 3, v243
	v_cmp_eq_u32_e64 s[14:15], 0, v243
	s_nop 3
	v_cndmask_b32_e64 v34, 0, 1.0, s[14:15]
	v_cmp_eq_u32_e64 s[14:15], 2, v243
	s_nop 3
	v_cndmask_b32_e64 v34, v34, -1.0, s[14:15]
	v_cmp_eq_u32_e64 s[14:15], 1, v243
	s_nop 3
	v_cndmask_b32_e64 v35, 0, -1.0, s[14:15]
	v_cmp_eq_u32_e64 s[14:15], 3, v243
	s_nop 3
	v_cndmask_b32_e64 v35, v35, 1.0, s[14:15]
	v_pk_mul_f32 v[36:37], v[32:33], v[34:35] op_sel:[1,1] op_sel_hi:[1,0]
	s_nop 0
	v_pk_fma_f32 v[228:229], v[32:33], v[34:35], v[36:37] op_sel_hi:[0,1,1] neg_lo:[0,0,1]
	s_nop 0
	v_add_u32_e32 v242, 1, v241
	v_and_b32_e32 v242, 3, v242
	v_mov_b32_e32 v32, 1.0
	v_mov_b32_e32 v33, 0
	v_cmp_eq_u32_e64 s[14:15], 1, v242
	s_nop 3
	v_cndmask_b32_e64 v32, v32, v218, s[14:15]
	v_cndmask_b32_e64 v33, v33, v219, s[14:15]
	v_cmp_eq_u32_e64 s[14:15], 2, v242
	s_nop 3
	v_cndmask_b32_e64 v32, v32, v220, s[14:15]
	v_cndmask_b32_e64 v33, v33, v221, s[14:15]
	v_cmp_eq_u32_e64 s[14:15], 3, v242
	s_nop 3
	v_cndmask_b32_e64 v32, v32, v30, s[14:15]
	v_cndmask_b32_e64 v33, v33, v31, s[14:15]
	v_add_u32_e32 v243, 1, v241
	v_mul_u32_u24_e32 v243, v243, v241
	v_and_b32_e32 v243, 3, v243
	v_cmp_eq_u32_e64 s[14:15], 0, v243
	s_nop 3
	v_cndmask_b32_e64 v34, 0, 1.0, s[14:15]
	v_cmp_eq_u32_e64 s[14:15], 2, v243
	s_nop 3
	v_cndmask_b32_e64 v34, v34, -1.0, s[14:15]
	v_cmp_eq_u32_e64 s[14:15], 1, v243
	s_nop 3
	v_cndmask_b32_e64 v35, 0, -1.0, s[14:15]
; DI float2 twid(float r) { return float2{__builtin_amdgcn_cosf(r), -__builtin_amdgcn_sinf(r)}; }
; DI void bfly_fwd(float2 a0, float2 a1, float2 a2, float2 a3, float r, float2& o0, float2& o1, float2& o2, float2& o3) {
;   float2 t0 = {a0.x + a2.x, a0.y + a2.y}, t1 = {a0.x - a2.x, a0.y - a2.y}, t2 = {a1.x + a3.x, a1.y + a3.y}, t3 = {a1.x - a3.x, a1.y - a3.y};
;   float2 b0 = {t0.x + t2.x, t0.y + t2.y}, b2 = {t0.x - t2.x, t0.y - t2.y}, b1 = {t1.x + t3.y, t1.y - t3.x}, b3 = {t1.x - t3.y, t1.y + t3.x};
;   float2 w1 = twid(r), w2 = cmul(w1, w1), w3 = cmul(w2, w1);
;   o0 = b0; o1 = cmul(b1, w1); o2 = cmul(b2, w2); o3 = cmul(b3, w3);
; }
;     ...
;   for (int bb = tid; bb < NBT * (N / 4); bb += NTHR) { const int b = bb & (N / 4 - 1); float2* z = z0 + (bb / (N / 4)) * N; int j = b & (Q - 1), base = ((b >> lq) << (lq + 2)) + j; float2 o0, o1, o2, o3;
;     bfly_fwd(z[base], z[base + Q], z[base + 2 * Q], z[base + 3 * Q], (float)j * invM, o0, o1, o2, o3);
;     z[base] = o0; z[base + Q] = o1; z[base + 2 * Q] = o2; z[base + 3 * Q] = o3; }
	v_cmp_eq_u32_e64 s[14:15], 3, v243
	s_nop 3
	v_cndmask_b32_e64 v35, v35, 1.0, s[14:15]
	v_pk_mul_f32 v[36:37], v[32:33], v[34:35] op_sel:[1,1] op_sel_hi:[1,0]
	s_nop 0
	v_pk_fma_f32 v[230:231], v[32:33], v[34:35], v[36:37] op_sel_hi:[0,1,1] neg_lo:[0,0,1]
	s_nop 0
	v_add_u32_e32 v242, 2, v241
	v_and_b32_e32 v242, 3, v242
	v_mov_b32_e32 v32, 1.0
	v_mov_b32_e32 v33, 0
	v_cmp_eq_u32_e64 s[14:15], 1, v242
	s_nop 3
	v_cndmask_b32_e64 v32, v32, v218, s[14:15]
	v_cndmask_b32_e64 v33, v33, v219, s[14:15]
	v_cmp_eq_u32_e64 s[14:15], 2, v242
	s_nop 3
	v_cndmask_b32_e64 v32, v32, v220, s[14:15]
	v_cndmask_b32_e64 v33, v33, v221, s[14:15]
	v_cmp_eq_u32_e64 s[14:15], 3, v242
	s_nop 3
	v_cndmask_b32_e64 v32, v32, v30, s[14:15]
	v_cndmask_b32_e64 v33, v33, v31, s[14:15]
	v_add_u32_e32 v243, 2, v241
	v_mul_u32_u24_e32 v243, v243, v241
	v_and_b32_e32 v243, 3, v243
	v_cmp_eq_u32_e64 s[14:15], 0, v243
	s_nop 3
	v_cndmask_b32_e64 v34, 0, 1.0, s[14:15]
	v_cmp_eq_u32_e64 s[14:15], 2, v243
	s_nop 3
	v_cndmask_b32_e64 v34, v34, -1.0, s[14:15]
	v_cmp_eq_u32_e64 s[14:15], 1, v243
	s_nop 3
	v_cndmask_b32_e64 v35, 0, -1.0, s[14:15]
	v_cmp_eq_u32_e64 s[14:15], 3, v243
	s_nop 3
	v_cndmask_b32_e64 v35, v35, 1.0, s[14:15]
	v_pk_mul_f32 v[36:37], v[32:33], v[34:35] op_sel:[1,1] op_sel_hi:[1,0]
	s_nop 0
	v_pk_fma_f32 v[232:233], v[32:33], v[34:35], v[36:37] op_sel_hi:[0,1,1] neg_lo:[0,0,1]
	s_nop 0
	v_add_u32_e32 v242, 3, v241
	v_and_b32_e32 v242, 3, v242
	v_mov_b32_e32 v32, 1.0
	v_mov_b32_e32 v33, 0
	v_cmp_eq_u32_e64 s[14:15], 1, v242
	s_nop 3
	v_cndmask_b32_e64 v32, v32, v218, s[14:15]
	v_cndmask_b32_e64 v33, v33, v219, s[14:15]
	v_cmp_eq_u32_e64 s[14:15], 2, v242
	s_nop 3
	v_cndmask_b32_e64 v32, v32, v220, s[14:15]
	v_cndmask_b32_e64 v33, v33, v221, s[14:15]
	v_cmp_eq_u32_e64 s[14:15], 3, v242
	s_nop 3
	v_cndmask_b32_e64 v32, v32, v30, s[14:15]
	v_cndmask_b32_e64 v33, v33, v31, s[14:15]
	v_add_u32_e32 v243, 3, v241
	v_mul_u32_u24_e32 v243, v243, v241
	v_and_b32_e32 v243, 3, v243
	v_cmp_eq_u32_e64 s[14:15], 0, v243
	s_nop 3
	v_cndmask_b32_e64 v34, 0, 1.0, s[14:15]
	v_cmp_eq_u32_e64 s[14:15], 2, v243
	s_nop 3
	v_cndmask_b32_e64 v34, v34, -1.0, s[14:15]
	v_cmp_eq_u32_e64 s[14:15], 1, v243
	s_nop 3
	v_cndmask_b32_e64 v35, 0, -1.0, s[14:15]
	v_cmp_eq_u32_e64 s[14:15], 3, v243
	s_nop 3
	v_cndmask_b32_e64 v35, v35, 1.0, s[14:15]
	v_pk_mul_f32 v[36:37], v[32:33], v[34:35] op_sel:[1,1] op_sel_hi:[1,0]
	s_nop 0
	v_pk_fma_f32 v[234:235], v[32:33], v[34:35], v[36:37] op_sel_hi:[0,1,1] neg_lo:[0,0,1]
	s_nop 0
.LBB0_1638:
	v_ashrrev_i32_e32 v21, 31, v20
	v_lshrrev_b32_e32 v21, 20, v21
	v_add_lshl_u32 v21, v20, v21, 5
	v_and_b32_e32 v21, 0xfffe0000, v21
	v_and_b32_e32 v22, 0x3ff0, v19
	v_add_u32_e32 v21, 16, v21
	v_lshlrev_b32_e32 v22, 3, v22
	v_lshlrev_b32_e32 v23, 3, v16
	v_add3_u32 v21, v21, v22, v23
	v_add_u32_e32 v241, v21, v236
	v_add_u32_e32 v242, v21, v237
	v_add_u32_e32 v243, v21, v238
	v_add_u32_e32 v244, v21, v239
	ds_read_b64 v[22:23], v241
	ds_read_b64 v[24:25], v242
	ds_read_b64 v[26:27], v243
	ds_read_b64 v[28:29], v244
	v_cmp_lt_i32_e64 s[14:15], s25, v20
	v_add_u32_e32 v19, 0x800, v19
	s_or_b64 s[80:81], s[14:15], s[80:81]
	s_waitcnt lgkmcnt(0)
	v_pk_mul_f32 v[218:219], v[24:25], v[222:223] op_sel:[1,1] op_sel_hi:[1,0]
	v_pk_mul_f32 v[220:221], v[26:27], v[224:225] op_sel:[1,1] op_sel_hi:[1,0]
	v_pk_mul_f32 v[30:31], v[28:29], v[226:227] op_sel:[1,1] op_sel_hi:[1,0]
	v_pk_fma_f32 v[24:25], v[24:25], v[222:223], v[218:219] op_sel_hi:[0,1,1] neg_lo:[0,0,1]
	v_pk_fma_f32 v[26:27], v[26:27], v[224:225], v[220:221] op_sel_hi:[0,1,1] neg_lo:[0,0,1]
	v_pk_fma_f32 v[28:29], v[28:29], v[226:227], v[30:31] op_sel_hi:[0,1,1] neg_lo:[0,0,1]
	v_pk_add_f32 v[30:31], v[22:23], v[26:27]
	v_pk_add_f32 v[32:33], v[22:23], v[26:27] neg_lo:[0,1] neg_hi:[0,1]
	v_pk_add_f32 v[34:35], v[24:25], v[28:29]
	v_pk_add_f32 v[36:37], v[24:25], v[28:29] neg_lo:[0,1] neg_hi:[0,1]
	v_pk_add_f32 v[22:23], v[30:31], v[34:35]
	v_pk_add_f32 v[26:27], v[30:31], v[34:35] neg_lo:[0,1] neg_hi:[0,1]
	v_pk_add_f32 v[24:25], v[32:33], v[36:37] op_sel:[0,1] op_sel_hi:[1,0] neg_hi:[0,1]
	v_pk_add_f32 v[28:29], v[32:33], v[36:37] op_sel:[0,1] op_sel_hi:[1,0] neg_lo:[0,1]
	v_pk_mul_f32 v[218:219], v[22:23], v[228:229] op_sel:[1,1] op_sel_hi:[1,0]
	v_pk_mul_f32 v[220:221], v[26:27], v[232:233] op_sel:[1,1] op_sel_hi:[1,0]
	v_pk_mul_f32 v[30:31], v[24:25], v[230:231] op_sel:[1,1] op_sel_hi:[1,0]
	v_pk_mul_f32 v[34:35], v[28:29], v[234:235] op_sel:[1,1] op_sel_hi:[1,0]
	v_pk_fma_f32 v[22:23], v[22:23], v[228:229], v[218:219] op_sel_hi:[0,1,1] neg_lo:[0,0,1]
	v_pk_fma_f32 v[26:27], v[26:27], v[232:233], v[220:221] op_sel_hi:[0,1,1] neg_lo:[0,0,1]
	v_pk_fma_f32 v[24:25], v[24:25], v[230:231], v[30:31] op_sel_hi:[0,1,1] neg_lo:[0,0,1]
	v_pk_fma_f32 v[28:29], v[28:29], v[234:235], v[34:35] op_sel_hi:[0,1,1] neg_lo:[0,0,1]
	s_nop 0
	ds_write_b64 v241, v[22:23]
	ds_write_b64 v243, v[26:27]
	ds_write_b64 v242, v[24:25]
	ds_write_b64 v244, v[28:29]
	v_add_u32_e32 v21, 0x200, v20
	v_mov_b32_e32 v20, v21
	s_andn2_b64 exec, exec, s[80:81]
	s_cbranch_execnz .LBB0_1638

; DI float2 twid(float r) { return float2{__builtin_amdgcn_cosf(r), -__builtin_amdgcn_sinf(r)}; }
; DI void bfly_inv(float2 s0, float2 s1, float2 s2, float2 s3, float r, float2& o0, float2& o1, float2& o2, float2& o3) {
;   float2 w1 = twid(r), w2 = cmul(w1, w1), w3 = cmul(w2, w1);
;   float2 c0 = s0, c1 = cmulc(s1, w1), c2 = cmulc(s2, w2), c3 = cmulc(s3, w3);
;   const int Q = 1 << lq; const float invM = 1.f / (float)(4 << lq);
;   for (int bb = tid; bb < NBT * (N / 4); bb += NTHR) { const int b = bb & (N / 4 - 1); float2* z = z0 + (bb / (N / 4)) * N; int j = b & (Q - 1), base = ((b >> lq) << (lq + 2)) + j; float2 o0, o1, o2, o3;
;     bfly_inv(z[base], z[base + Q], z[base + 2 * Q], z[base + 3 * Q], (float)j * invM, o0, o1, o2, o3);
.LBB0_1645:
	s_or_b64 exec, exec, s[0:1]
	s_waitcnt lgkmcnt(0)
	s_barrier
	s_and_saveexec_b64 s[0:1], s[12:13]
	s_cbranch_execz .LBB0_1648
	v_mul_f32_e32 v4, 0x3d800000, v18
	v_sin_f32_e32 v5, v4
	v_cos_f32_e32 v7, v4
	s_mov_b64 s[14:15], 0
	v_mov_b32_e32 v18, v76
	v_mul_f32_e32 v4, v5, v5
	v_mul_f32_e64 v6, v7, -v5
	v_fma_f32 v8, v7, v7, -v4
	v_add_f32_e32 v10, v6, v6
	v_mul_f32_e32 v4, v5, v10
	v_mul_f32_e32 v6, v5, v8
	v_fmac_f32_e32 v4, v7, v8
	v_fma_f32 v6, v7, v10, -v6
	v_mov_b32_e32 v9, v8
	v_pk_mov_b32 v[12:13], v[6:7], v[4:5] op_sel:[1,0]
	v_pk_mov_b32 v[14:15], v[4:5], v[6:7] op_sel:[1,0]
	v_mov_b32_e32 v11, v10
	v_and_b32_e32 v248, 3, v18
	v_cvt_f32_u32_e32 v248, v248
	v_mul_f32_e32 v248, 0x3d800000, v248
	v_cos_f32_e32 v220, v248
	v_sin_f32_e32 v221, v248
	s_nop 1
	v_xor_b32_e32 v221, 0x80000000, v221
	s_nop 0
	v_pk_mul_f32 v[218:219], v[220:221], v[220:221] op_sel:[1,1] op_sel_hi:[1,0]
	s_nop 0
	v_pk_fma_f32 v[222:223], v[220:221], v[220:221], v[218:219] op_sel_hi:[0,1,1] neg_lo:[0,0,1]
	s_nop 0
	v_pk_mul_f32 v[218:219], v[222:223], v[220:221] op_sel:[1,1] op_sel_hi:[1,0]
	s_nop 0
	v_pk_fma_f32 v[28:29], v[222:223], v[220:221], v[218:219] op_sel_hi:[0,1,1] neg_lo:[0,0,1]
	s_nop 0
	v_bfe_u32 v245, v18, 2, 2
	v_bfe_u32 v248, v18, 4, 1
	v_add_u32_e32 v245, v245, v248
	v_and_b32_e32 v245, 3, v245
	v_add_u32_e32 v248, 0, v245
	v_and_b32_e32 v248, 3, v248
	v_lshlrev_b32_e32 v241, 5, v248
	v_add_u32_e32 v248, 1, v245
	v_and_b32_e32 v248, 3, v248
	v_lshlrev_b32_e32 v242, 5, v248
	v_add_u32_e32 v248, 2, v245
	v_and_b32_e32 v248, 3, v248
	v_lshlrev_b32_e32 v243, 5, v248
	v_add_u32_e32 v248, 3, v245
	v_and_b32_e32 v248, 3, v248
	v_lshlrev_b32_e32 v244, 5, v248
	v_add_u32_e32 v246, 0, v245
	v_and_b32_e32 v246, 3, v246
	v_mov_b32_e32 v30, 1.0
	v_mov_b32_e32 v31, 0
	v_cmp_eq_u32_e64 s[12:13], 1, v246
	s_nop 3
	v_cndmask_b32_e64 v30, v30, v220, s[12:13]
	v_cndmask_b32_e64 v31, v31, v221, s[12:13]
	v_cmp_eq_u32_e64 s[12:13], 2, v246
	s_nop 3
	v_cndmask_b32_e64 v30, v30, v222, s[12:13]
	v_cndmask_b32_e64 v31, v31, v223, s[12:13]
	v_cmp_eq_u32_e64 s[12:13], 3, v246
	s_nop 3
	v_cndmask_b32_e64 v30, v30, v28, s[12:13]
	v_cndmask_b32_e64 v31, v31, v29, s[12:13]
	v_xor_b32_e32 v31, 0x80000000, v31
	v_mul_u32_u24_e32 v247, 0, v245
	v_and_b32_e32 v247, 3, v247
	v_cmp_eq_u32_e64 s[12:13], 0, v247
	s_nop 3
	v_cndmask_b32_e64 v32, 0, 1.0, s[12:13]
	v_cmp_eq_u32_e64 s[12:13], 2, v247
	s_nop 3
	v_cndmask_b32_e64 v32, v32, -1.0, s[12:13]
	v_cmp_eq_u32_e64 s[12:13], 1, v247
	s_nop 3
	v_cndmask_b32_e64 v33, 0, 1.0, s[12:13]
	v_cmp_eq_u32_e64 s[12:13], 3, v247
	s_nop 3
	v_cndmask_b32_e64 v33, v33, -1.0, s[12:13]
	v_pk_mul_f32 v[218:219], v[30:31], v[32:33] op_sel:[1,1] op_sel_hi:[1,0]
	s_nop 0
	v_pk_fma_f32 v[224:225], v[30:31], v[32:33], v[218:219] op_sel_hi:[0,1,1] neg_lo:[0,0,1]
	s_nop 0
	v_add_u32_e32 v246, 1, v245
	v_and_b32_e32 v246, 3, v246
	v_mov_b32_e32 v30, 1.0
	v_mov_b32_e32 v31, 0
	v_cmp_eq_u32_e64 s[12:13], 1, v246
	s_nop 3
	v_cndmask_b32_e64 v30, v30, v220, s[12:13]
	v_cndmask_b32_e64 v31, v31, v221, s[12:13]
	v_cmp_eq_u32_e64 s[12:13], 2, v246
	s_nop 3
	v_cndmask_b32_e64 v30, v30, v222, s[12:13]
	v_cndmask_b32_e64 v31, v31, v223, s[12:13]
	v_cmp_eq_u32_e64 s[12:13], 3, v246
	s_nop 3
	v_cndmask_b32_e64 v30, v30, v28, s[12:13]
	v_cndmask_b32_e64 v31, v31, v29, s[12:13]
	v_xor_b32_e32 v31, 0x80000000, v31
	v_mul_u32_u24_e32 v247, 1, v245
	v_and_b32_e32 v247, 3, v247
	v_cmp_eq_u32_e64 s[12:13], 0, v247
	s_nop 3
	v_cndmask_b32_e64 v32, 0, 1.0, s[12:13]
	v_cmp_eq_u32_e64 s[12:13], 2, v247
	s_nop 3
	v_cndmask_b32_e64 v32, v32, -1.0, s[12:13]
	v_cmp_eq_u32_e64 s[12:13], 1, v247
	s_nop 3
	v_cndmask_b32_e64 v33, 0, 1.0, s[12:13]
	v_cmp_eq_u32_e64 s[12:13], 3, v247
	s_nop 3
	v_cndmask_b32_e64 v33, v33, -1.0, s[12:13]
	v_pk_mul_f32 v[218:219], v[30:31], v[32:33] op_sel:[1,1] op_sel_hi:[1,0]
	s_nop 0
	v_pk_fma_f32 v[226:227], v[30:31], v[32:33], v[218:219] op_sel_hi:[0,1,1] neg_lo:[0,0,1]
	s_nop 0
	v_add_u32_e32 v246, 2, v245
	v_and_b32_e32 v246, 3, v246
	v_mov_b32_e32 v30, 1.0
	v_mov_b32_e32 v31, 0
	v_cmp_eq_u32_e64 s[12:13], 1, v246
	s_nop 3
	v_cndmask_b32_e64 v30, v30, v220, s[12:13]
	v_cndmask_b32_e64 v31, v31, v221, s[12:13]
	v_cmp_eq_u32_e64 s[12:13], 2, v246
	s_nop 3
	v_cndmask_b32_e64 v30, v30, v222, s[12:13]
	v_cndmask_b32_e64 v31, v31, v223, s[12:13]
	v_cmp_eq_u32_e64 s[12:13], 3, v246
	s_nop 3
	v_cndmask_b32_e64 v30, v30, v28, s[12:13]
	v_cndmask_b32_e64 v31, v31, v29, s[12:13]
	v_xor_b32_e32 v31, 0x80000000, v31
	v_mul_u32_u24_e32 v247, 2, v245
	v_and_b32_e32 v247, 3, v247
	v_cmp_eq_u32_e64 s[12:13], 0, v247
	s_nop 3
	v_cndmask_b32_e64 v32, 0, 1.0, s[12:13]
	v_cmp_eq_u32_e64 s[12:13], 2, v247
	s_nop 3
	v_cndmask_b32_e64 v32, v32, -1.0, s[12:13]
	v_cmp_eq_u32_e64 s[12:13], 1, v247
	s_nop 3
	v_cndmask_b32_e64 v33, 0, 1.0, s[12:13]
	v_cmp_eq_u32_e64 s[12:13], 3, v247
	s_nop 3
	v_cndmask_b32_e64 v33, v33, -1.0, s[12:13]
	v_pk_mul_f32 v[218:219], v[30:31], v[32:33] op_sel:[1,1] op_sel_hi:[1,0]
	s_nop 0
	v_pk_fma_f32 v[228:229], v[30:31], v[32:33], v[218:219] op_sel_hi:[0,1,1] neg_lo:[0,0,1]
	s_nop 0
	v_add_u32_e32 v246, 3, v245
	v_and_b32_e32 v246, 3, v246
	v_mov_b32_e32 v30, 1.0
	v_mov_b32_e32 v31, 0
	v_cmp_eq_u32_e64 s[12:13], 1, v246
	s_nop 3
	v_cndmask_b32_e64 v30, v30, v220, s[12:13]
	v_cndmask_b32_e64 v31, v31, v221, s[12:13]
	v_cmp_eq_u32_e64 s[12:13], 2, v246
	s_nop 3
; DI float2 twid(float r) { return float2{__builtin_amdgcn_cosf(r), -__builtin_amdgcn_sinf(r)}; }
; DI void bfly_inv(float2 s0, float2 s1, float2 s2, float2 s3, float r, float2& o0, float2& o1, float2& o2, float2& o3) {
;   float2 w1 = twid(r), w2 = cmul(w1, w1), w3 = cmul(w2, w1);
;   float2 c0 = s0, c1 = cmulc(s1, w1), c2 = cmulc(s2, w2), c3 = cmulc(s3, w3);
;   float2 t0 = {c0.x + c2.x, c0.y + c2.y}, t1 = {c0.x - c2.x, c0.y - c2.y}, t2 = {c1.x + c3.x, c1.y + c3.y}, t3 = {c1.x - c3.x, c1.y - c3.y};
;   o0 = float2{t0.x + t2.x, t0.y + t2.y}; o2 = float2{t0.x - t2.x, t0.y - t2.y}; o1 = float2{t1.x - t3.y, t1.y + t3.x}; o3 = float2{t1.x + t3.y, t1.y - t3.x};
; }
;     ...
;   for (int bb = tid; bb < NBT * (N / 4); bb += NTHR) { const int b = bb & (N / 4 - 1); float2* z = z0 + (bb / (N / 4)) * N; int j = b & (Q - 1), base = ((b >> lq) << (lq + 2)) + j; float2 o0, o1, o2, o3;
;     bfly_inv(z[base], z[base + Q], z[base + 2 * Q], z[base + 3 * Q], (float)j * invM, o0, o1, o2, o3);
;     z[base] = o0; z[base + Q] = o1; z[base + 2 * Q] = o2; z[base + 3 * Q] = o3; }
	v_cndmask_b32_e64 v30, v30, v222, s[12:13]
	v_cndmask_b32_e64 v31, v31, v223, s[12:13]
	v_cmp_eq_u32_e64 s[12:13], 3, v246
	s_nop 3
	v_cndmask_b32_e64 v30, v30, v28, s[12:13]
	v_cndmask_b32_e64 v31, v31, v29, s[12:13]
	v_xor_b32_e32 v31, 0x80000000, v31
	v_mul_u32_u24_e32 v247, 3, v245
	v_and_b32_e32 v247, 3, v247
	v_cmp_eq_u32_e64 s[12:13], 0, v247
	s_nop 3
	v_cndmask_b32_e64 v32, 0, 1.0, s[12:13]
	v_cmp_eq_u32_e64 s[12:13], 2, v247
	s_nop 3
	v_cndmask_b32_e64 v32, v32, -1.0, s[12:13]
	v_cmp_eq_u32_e64 s[12:13], 1, v247
	s_nop 3
	v_cndmask_b32_e64 v33, 0, 1.0, s[12:13]
	v_cmp_eq_u32_e64 s[12:13], 3, v247
	s_nop 3
	v_cndmask_b32_e64 v33, v33, -1.0, s[12:13]
	v_pk_mul_f32 v[218:219], v[30:31], v[32:33] op_sel:[1,1] op_sel_hi:[1,0]
	s_nop 0
	v_pk_fma_f32 v[230:231], v[30:31], v[32:33], v[218:219] op_sel_hi:[0,1,1] neg_lo:[0,0,1]
	s_nop 0
	v_add_u32_e32 v247, 0, v245
	v_mul_u32_u24_e32 v247, v247, v245
	v_and_b32_e32 v247, 3, v247
	v_cmp_eq_u32_e64 s[12:13], 0, v247
	s_nop 3
	v_cndmask_b32_e64 v232, 0, 1.0, s[12:13]
	v_cmp_eq_u32_e64 s[12:13], 2, v247
	s_nop 3
	v_cndmask_b32_e64 v232, v232, -1.0, s[12:13]
	v_cmp_eq_u32_e64 s[12:13], 1, v247
	s_nop 3
	v_cndmask_b32_e64 v233, 0, 1.0, s[12:13]
	v_cmp_eq_u32_e64 s[12:13], 3, v247
	s_nop 3
	v_cndmask_b32_e64 v233, v233, -1.0, s[12:13]
	v_add_u32_e32 v247, 1, v245
	v_mul_u32_u24_e32 v247, v247, v245
	v_and_b32_e32 v247, 3, v247
	v_cmp_eq_u32_e64 s[12:13], 0, v247
	s_nop 3
	v_cndmask_b32_e64 v234, 0, 1.0, s[12:13]
	v_cmp_eq_u32_e64 s[12:13], 2, v247
	s_nop 3
	v_cndmask_b32_e64 v234, v234, -1.0, s[12:13]
	v_cmp_eq_u32_e64 s[12:13], 1, v247
	s_nop 3
	v_cndmask_b32_e64 v235, 0, 1.0, s[12:13]
	v_cmp_eq_u32_e64 s[12:13], 3, v247
	s_nop 3
	v_cndmask_b32_e64 v235, v235, -1.0, s[12:13]
	v_add_u32_e32 v247, 2, v245
	v_mul_u32_u24_e32 v247, v247, v245
	v_and_b32_e32 v247, 3, v247
	v_cmp_eq_u32_e64 s[12:13], 0, v247
	s_nop 3
	v_cndmask_b32_e64 v236, 0, 1.0, s[12:13]
	v_cmp_eq_u32_e64 s[12:13], 2, v247
	s_nop 3
	v_cndmask_b32_e64 v236, v236, -1.0, s[12:13]
	v_cmp_eq_u32_e64 s[12:13], 1, v247
	s_nop 3
	v_cndmask_b32_e64 v237, 0, 1.0, s[12:13]
	v_cmp_eq_u32_e64 s[12:13], 3, v247
	s_nop 3
	v_cndmask_b32_e64 v237, v237, -1.0, s[12:13]
	v_add_u32_e32 v247, 3, v245
	v_mul_u32_u24_e32 v247, v247, v245
	v_and_b32_e32 v247, 3, v247
	v_cmp_eq_u32_e64 s[12:13], 0, v247
	s_nop 3
	v_cndmask_b32_e64 v238, 0, 1.0, s[12:13]
	v_cmp_eq_u32_e64 s[12:13], 2, v247
	s_nop 3
	v_cndmask_b32_e64 v238, v238, -1.0, s[12:13]
	v_cmp_eq_u32_e64 s[12:13], 1, v247
	s_nop 3
	v_cndmask_b32_e64 v239, 0, 1.0, s[12:13]
	v_cmp_eq_u32_e64 s[12:13], 3, v247
	s_nop 3
	v_cndmask_b32_e64 v239, v239, -1.0, s[12:13]
.LBB0_1647:
	v_ashrrev_i32_e32 v19, 31, v18
	v_lshrrev_b32_e32 v19, 20, v19
	v_add_lshl_u32 v19, v18, v19, 5
	v_and_b32_e32 v19, 0xfffe0000, v19
	v_and_b32_e32 v20, 0x3ff0, v17
	v_add_u32_e32 v19, 16, v19
	v_lshlrev_b32_e32 v20, 3, v20
	v_lshlrev_b32_e32 v21, 3, v16
	v_add3_u32 v19, v19, v20, v21
	v_add_u32_e32 v245, v19, v241
	v_add_u32_e32 v246, v19, v242
	v_add_u32_e32 v247, v19, v243
	v_add_u32_e32 v248, v19, v244
	ds_read_b64 v[20:21], v245
	ds_read_b64 v[22:23], v246
	ds_read_b64 v[24:25], v247
	ds_read_b64 v[26:27], v248
	v_cmp_lt_i32_e64 s[12:13], s25, v18
	v_add_u32_e32 v17, 0x800, v17
	s_or_b64 s[14:15], s[12:13], s[14:15]
	s_waitcnt lgkmcnt(0)
	v_pk_mul_f32 v[220:221], v[20:21], v[224:225] op_sel:[1,1] op_sel_hi:[1,0]
	v_pk_mul_f32 v[222:223], v[22:23], v[226:227] op_sel:[1,1] op_sel_hi:[1,0]
	v_pk_mul_f32 v[28:29], v[24:25], v[228:229] op_sel:[1,1] op_sel_hi:[1,0]
	v_pk_mul_f32 v[30:31], v[26:27], v[230:231] op_sel:[1,1] op_sel_hi:[1,0]
	v_pk_fma_f32 v[20:21], v[20:21], v[224:225], v[220:221] op_sel_hi:[0,1,1] neg_lo:[0,0,1]
	v_pk_fma_f32 v[22:23], v[22:23], v[226:227], v[222:223] op_sel_hi:[0,1,1] neg_lo:[0,0,1]
	v_pk_fma_f32 v[24:25], v[24:25], v[228:229], v[28:29] op_sel_hi:[0,1,1] neg_lo:[0,0,1]
	v_pk_fma_f32 v[26:27], v[26:27], v[230:231], v[30:31] op_sel_hi:[0,1,1] neg_lo:[0,0,1]
	v_pk_add_f32 v[28:29], v[20:21], v[24:25]
	v_pk_add_f32 v[30:31], v[20:21], v[24:25] neg_lo:[0,1] neg_hi:[0,1]
	v_pk_add_f32 v[32:33], v[22:23], v[26:27]
	v_pk_add_f32 v[218:219], v[22:23], v[26:27] neg_lo:[0,1] neg_hi:[0,1]
	v_pk_add_f32 v[20:21], v[28:29], v[32:33]
	v_pk_add_f32 v[24:25], v[28:29], v[32:33] neg_lo:[0,1] neg_hi:[0,1]
	v_pk_add_f32 v[22:23], v[30:31], v[218:219] op_sel:[0,1] op_sel_hi:[1,0] neg_lo:[0,1]
	v_pk_add_f32 v[26:27], v[30:31], v[218:219] op_sel:[0,1] op_sel_hi:[1,0] neg_hi:[0,1]
	v_pk_mul_f32 v[220:221], v[20:21], v[232:233] op_sel:[1,1] op_sel_hi:[1,0]
	v_pk_mul_f32 v[222:223], v[24:25], v[236:237] op_sel:[1,1] op_sel_hi:[1,0]
	v_pk_mul_f32 v[28:29], v[22:23], v[234:235] op_sel:[1,1] op_sel_hi:[1,0]
	v_pk_mul_f32 v[32:33], v[26:27], v[238:239] op_sel:[1,1] op_sel_hi:[1,0]
	v_pk_fma_f32 v[20:21], v[20:21], v[232:233], v[220:221] op_sel_hi:[0,1,1] neg_lo:[0,0,1]
	v_pk_fma_f32 v[24:25], v[24:25], v[236:237], v[222:223] op_sel_hi:[0,1,1] neg_lo:[0,0,1]
	v_pk_fma_f32 v[22:23], v[22:23], v[234:235], v[28:29] op_sel_hi:[0,1,1] neg_lo:[0,0,1]
	v_pk_fma_f32 v[26:27], v[26:27], v[238:239], v[32:33] op_sel_hi:[0,1,1] neg_lo:[0,0,1]
	s_nop 0
	ds_write_b64 v245, v[20:21]
	ds_write_b64 v247, v[24:25]
	ds_write_b64 v246, v[22:23]
	ds_write_b64 v248, v[26:27]
	v_add_u32_e32 v19, 0x200, v18
	v_mov_b32_e32 v18, v19
	s_andn2_b64 exec, exec, s[14:15]
	s_cbranch_execnz .LBB0_1647
